# P0 x-conversion loop next-row prefetch + EM_RES residual loads hoisted above align barrier
# baseline (speedup 1.0000x reference)
.LBB0_49:
	s_mov_b64 s[4:5], s[0:1]
	s_mov_b64 s[10:11], s[0:1]
	s_mov_b64 s[6:7], s[0:1]
	s_load_dwordx2 s[8:9], s[6:7], 0xa8
	s_mov_b64 s[6:7], s[0:1]
	s_load_dwordx2 s[6:7], s[6:7], 0xa8
	s_cmpk_gt_i32 s28, 0x7fff
	s_movk_i32 s26, 0x7fff
	s_cbranch_scc1 .LBB0_54
	v_mbcnt_lo_u32_b32 v2, -1, 0
	v_mbcnt_hi_u32_b32 v2, -1, v2
	v_and_b32_e32 v3, 64, v2
	v_add_u32_e32 v3, 64, v3
	v_xor_b32_e32 v4, 1, v2
	v_cmp_lt_i32_e32 vcc, v4, v3
	s_load_dwordx2 s[16:17], s[4:5], 0x0
	s_load_dwordx2 s[14:15], s[10:11], 0xa8
	v_cndmask_b32_e32 v4, v2, v4, vcc
	v_lshlrev_b32_e32 v8, 2, v4
	v_xor_b32_e32 v4, 2, v2
	v_cmp_lt_i32_e32 vcc, v4, v3
	s_ashr_i32 s29, s28, 31
	s_lshl_b64 s[4:5], s[28:29], 2
	v_cndmask_b32_e32 v4, v2, v4, vcc
	v_lshlrev_b32_e32 v9, 2, v4
	v_xor_b32_e32 v4, 4, v2
	v_cmp_lt_i32_e32 vcc, v4, v3
	s_waitcnt lgkmcnt(0)
	s_add_u32 s4, s8, s4
	s_addc_u32 s5, s9, s5
	v_cndmask_b32_e32 v4, v2, v4, vcc
	v_lshlrev_b32_e32 v10, 2, v4
	v_xor_b32_e32 v4, 8, v2
	v_cmp_lt_i32_e32 vcc, v4, v3
	s_ashr_i32 s31, s30, 31
	s_lshl_b64 s[10:11], s[30:31], 2
	v_cndmask_b32_e32 v4, v2, v4, vcc
	v_lshlrev_b32_e32 v11, 2, v4
	v_xor_b32_e32 v4, 16, v2
	v_cmp_lt_i32_e32 vcc, v4, v3
	s_lshl_b64 s[24:25], s[28:29], 11
	s_add_u32 s14, s14, s24
	v_cndmask_b32_e32 v4, v2, v4, vcc
	v_lshlrev_b32_e32 v12, 2, v4
	v_xor_b32_e32 v4, 32, v2
	v_cmp_lt_i32_e32 vcc, v4, v3
	v_mov_b32_e32 v3, 0
	s_addc_u32 s15, s15, s25
	v_cndmask_b32_e32 v2, v2, v4, vcc
	v_lshlrev_b32_e32 v13, 2, v2
	v_lshlrev_b32_e32 v2, 3, v242
	v_lshl_add_u64 v[4:5], s[14:15], 0, v[2:3]
	s_mov_b64 s[14:15], 0x6400600
	v_lshl_add_u64 v[4:5], v[4:5], 0, s[14:15]
	s_lshl_b64 s[14:15], s[30:31], 11
	s_lshl_b64 s[24:25], s[28:29], 12
	s_add_u32 s16, s16, s24
	v_lshlrev_b32_e32 v2, 4, v242
	s_addc_u32 s17, s17, s25
	v_lshl_add_u64 v[6:7], s[16:17], 0, v[2:3]
	s_mov_b64 s[16:17], 0x800
	v_cmp_eq_u32_e32 vcc, 0, v242
	v_lshl_add_u64 v[6:7], v[6:7], 0, s[16:17]
	s_lshl_b64 s[16:17], s[30:31], 12
	s_mov_b32 s27, 0xffff0000
	s_mov_b32 s29, s28
	global_load_dwordx4 v[14:17], v[6:7], off offset:-2048 nt
	global_load_dwordx4 v[18:21], v[6:7], off offset:-1024 nt
	global_load_dwordx4 v[22:25], v[6:7], off nt
	global_load_dwordx4 v[26:29], v[6:7], off offset:1024 nt
.Lx_A:
	v_lshl_add_u64 v[68:69], v[6:7], 0, s[16:17]
	s_add_i32 s98, s29, s30
	s_cmpk_gt_i32 s98, 0x7fff
	s_cbranch_scc1 .Lx_A_nopf
	global_load_dwordx4 v[52:55], v[68:69], off offset:-2048 nt
	global_load_dwordx4 v[56:59], v[68:69], off offset:-1024 nt
	global_load_dwordx4 v[60:63], v[68:69], off nt
	global_load_dwordx4 v[64:67], v[68:69], off offset:1024 nt
	s_waitcnt vmcnt(4)
	s_branch .Lx_A_body

.Lx_A_body:
	s_waitcnt lgkmcnt(0)
	v_mul_f32_e32 v2, v15, v15
	v_mul_f32_e32 v30, v17, v17
	v_mul_f32_e32 v31, v19, v19
	v_mul_f32_e32 v32, v21, v21
	v_mul_f32_e32 v33, v23, v23
	v_mul_f32_e32 v34, v25, v25
	v_fmac_f32_e32 v2, v14, v14
	v_fmac_f32_e32 v30, v16, v16
	v_fmac_f32_e32 v31, v18, v18
	v_fmac_f32_e32 v32, v20, v20
	v_mul_f32_e32 v35, v27, v27
	v_mul_f32_e32 v36, v29, v29
	v_fmac_f32_e32 v33, v22, v22
	v_fmac_f32_e32 v34, v24, v24
	v_add_f32_e32 v2, v2, v30
	v_add_f32_e32 v30, v31, v32
	v_fmac_f32_e32 v35, v26, v26
	v_fmac_f32_e32 v36, v28, v28
	v_add_f32_e32 v31, v33, v34
	v_add_f32_e32 v2, v2, v30
	v_add_f32_e32 v32, v35, v36
	v_add_f32_e32 v2, v2, v31
	v_add_f32_e32 v2, v2, v32
	ds_bpermute_b32 v30, v8, v2
	v_bfe_u32 v37, v14, 16, 1
	v_bfe_u32 v39, v16, 16, 1
	v_bfe_u32 v43, v20, 16, 1
	v_bfe_u32 v38, v15, 16, 1
	s_waitcnt lgkmcnt(0)
	v_add_f32_e32 v2, v2, v30
	ds_bpermute_b32 v30, v9, v2
	v_bfe_u32 v40, v17, 16, 1
	v_bfe_u32 v44, v21, 16, 1
	v_add3_u32 v14, v14, v37, s26
	v_add3_u32 v16, v16, v39, s26
	s_waitcnt lgkmcnt(0)
	v_add_f32_e32 v2, v2, v30
	ds_bpermute_b32 v30, v10, v2
	v_add3_u32 v20, v20, v43, s26
	v_add3_u32 v15, v15, v38, s26
	v_add3_u32 v17, v17, v40, s26
	v_add3_u32 v21, v21, v44, s26
	s_waitcnt lgkmcnt(0)
	v_add_f32_e32 v2, v2, v30
	ds_bpermute_b32 v30, v11, v2
	v_lshrrev_b32_e32 v14, 16, v14
	v_lshrrev_b32_e32 v16, 16, v16
	v_lshrrev_b32_e32 v20, 16, v20
	v_and_or_b32 v14, v15, s27, v14
	s_waitcnt lgkmcnt(0)
	v_add_f32_e32 v2, v2, v30
	v_and_or_b32 v15, v17, s27, v16
	v_and_or_b32 v17, v21, s27, v20
	v_mov_b32_e32 v21, v2
	s_nop 1
	v_permlane16_swap_b32_e32 v21, v2
	v_bfe_u32 v41, v18, 16, 1
	v_bfe_u32 v45, v22, 16, 1
	v_bfe_u32 v47, v24, 16, 1
	v_bfe_u32 v42, v19, 16, 1
	v_bfe_u32 v46, v23, 16, 1
	v_bfe_u32 v48, v25, 16, 1
	v_add3_u32 v18, v18, v41, s26
	v_add3_u32 v22, v22, v45, s26
	v_add3_u32 v24, v24, v47, s26
	v_add3_u32 v19, v19, v42, s26
	v_add3_u32 v23, v23, v46, s26
	v_add3_u32 v25, v25, v48, s26
	v_lshrrev_b32_e32 v18, 16, v18
	v_lshrrev_b32_e32 v22, 16, v22
	v_lshrrev_b32_e32 v24, 16, v24
	s_waitcnt lgkmcnt(0)
	v_add_f32_e32 v2, v2, v21
	v_and_or_b32 v16, v19, s27, v18
	v_and_or_b32 v18, v23, s27, v22
	v_and_or_b32 v19, v25, s27, v24
	global_store_dwordx2 v[4:5], v[14:15], off offset:-1536
	global_store_dwordx2 v[4:5], v[16:17], off offset:-1024
	global_store_dwordx2 v[4:5], v[18:19], off offset:-512
	v_mov_b32_e32 v14, v2
	s_nop 1
	v_permlane32_swap_b32_e32 v14, v2
	v_bfe_u32 v49, v26, 16, 1
	v_bfe_u32 v51, v28, 16, 1
	v_bfe_u32 v50, v27, 16, 1
	v_add3_u32 v26, v26, v49, s26
	v_add3_u32 v28, v28, v51, s26
	v_bfe_u32 v16, v29, 16, 1
	v_add3_u32 v27, v27, v50, s26
	v_lshrrev_b32_e32 v26, 16, v26
	v_lshrrev_b32_e32 v15, 16, v28
	v_add3_u32 v16, v29, v16, s26
	v_and_or_b32 v20, v27, s27, v26
	v_and_or_b32 v21, v16, s27, v15
	global_store_dwordx2 v[4:5], v[20:21], off
	s_and_saveexec_b64 s[24:25], vcc
	s_cbranch_execz .Lx_A_latch
	s_waitcnt lgkmcnt(0)
	v_add_f32_e32 v2, v2, v14
	global_store_dword v3, v2, s[4:5]
	s_branch .Lx_A_latch
.Lx_A_latch:
	s_or_b64 exec, exec, s[24:25]
	s_add_i32 s29, s29, s30
	s_add_u32 s4, s4, s10
	s_addc_u32 s5, s5, s11
	v_lshl_add_u64 v[4:5], v[4:5], 0, s[14:15]
	s_cmpk_gt_i32 s29, 0x7fff
	v_mov_b32_e32 v6, v68
	v_mov_b32_e32 v7, v69
	s_cbranch_scc1 .LBB0_54
.Lx_B:
	v_lshl_add_u64 v[68:69], v[6:7], 0, s[16:17]
	s_add_i32 s98, s29, s30
	s_cmpk_gt_i32 s98, 0x7fff
	s_cbranch_scc1 .Lx_B_nopf
	global_load_dwordx4 v[14:17], v[68:69], off offset:-2048 nt
	global_load_dwordx4 v[18:21], v[68:69], off offset:-1024 nt
	global_load_dwordx4 v[22:25], v[68:69], off nt
	global_load_dwordx4 v[26:29], v[68:69], off offset:1024 nt
	s_waitcnt vmcnt(4)
	s_branch .Lx_B_body

.Lx_B_body:
	s_waitcnt lgkmcnt(0)
	v_mul_f32_e32 v2, v53, v53
	v_mul_f32_e32 v30, v55, v55
	v_mul_f32_e32 v31, v57, v57
	v_mul_f32_e32 v32, v59, v59
	v_mul_f32_e32 v33, v61, v61
	v_mul_f32_e32 v34, v63, v63
	v_fmac_f32_e32 v2, v52, v52
	v_fmac_f32_e32 v30, v54, v54
	v_fmac_f32_e32 v31, v56, v56
	v_fmac_f32_e32 v32, v58, v58
	v_mul_f32_e32 v35, v65, v65
	v_mul_f32_e32 v36, v67, v67
	v_fmac_f32_e32 v33, v60, v60
	v_fmac_f32_e32 v34, v62, v62
	v_add_f32_e32 v2, v2, v30
	v_add_f32_e32 v30, v31, v32
	v_fmac_f32_e32 v35, v64, v64
	v_fmac_f32_e32 v36, v66, v66
	v_add_f32_e32 v31, v33, v34
	v_add_f32_e32 v2, v2, v30
	v_add_f32_e32 v32, v35, v36
	v_add_f32_e32 v2, v2, v31
	v_add_f32_e32 v2, v2, v32
	ds_bpermute_b32 v30, v8, v2
	v_bfe_u32 v37, v52, 16, 1
	v_bfe_u32 v39, v54, 16, 1
	v_bfe_u32 v43, v58, 16, 1
	v_bfe_u32 v38, v53, 16, 1
	s_waitcnt lgkmcnt(0)
	v_add_f32_e32 v2, v2, v30
	ds_bpermute_b32 v30, v9, v2
	v_bfe_u32 v40, v55, 16, 1
	v_bfe_u32 v44, v59, 16, 1
	v_add3_u32 v52, v52, v37, s26
	v_add3_u32 v54, v54, v39, s26
	s_waitcnt lgkmcnt(0)
	v_add_f32_e32 v2, v2, v30
	ds_bpermute_b32 v30, v10, v2
	v_add3_u32 v58, v58, v43, s26
	v_add3_u32 v53, v53, v38, s26
	v_add3_u32 v55, v55, v40, s26
	v_add3_u32 v59, v59, v44, s26
	s_waitcnt lgkmcnt(0)
	v_add_f32_e32 v2, v2, v30
	ds_bpermute_b32 v30, v11, v2
	v_lshrrev_b32_e32 v52, 16, v52
	v_lshrrev_b32_e32 v54, 16, v54
	v_lshrrev_b32_e32 v58, 16, v58
	v_and_or_b32 v52, v53, s27, v52
	s_waitcnt lgkmcnt(0)
	v_add_f32_e32 v2, v2, v30
	v_and_or_b32 v53, v55, s27, v54
	v_and_or_b32 v55, v59, s27, v58
	v_mov_b32_e32 v59, v2
	s_nop 1
	v_permlane16_swap_b32_e32 v59, v2
	v_bfe_u32 v41, v56, 16, 1
	v_bfe_u32 v45, v60, 16, 1
	v_bfe_u32 v47, v62, 16, 1
	v_bfe_u32 v42, v57, 16, 1
	v_bfe_u32 v46, v61, 16, 1
	v_bfe_u32 v48, v63, 16, 1
	v_add3_u32 v56, v56, v41, s26
	v_add3_u32 v60, v60, v45, s26
	v_add3_u32 v62, v62, v47, s26
	v_add3_u32 v57, v57, v42, s26
	v_add3_u32 v61, v61, v46, s26
	v_add3_u32 v63, v63, v48, s26
	v_lshrrev_b32_e32 v56, 16, v56
	v_lshrrev_b32_e32 v60, 16, v60
	v_lshrrev_b32_e32 v62, 16, v62
	s_waitcnt lgkmcnt(0)
	v_add_f32_e32 v2, v2, v59
	v_and_or_b32 v54, v57, s27, v56
	v_and_or_b32 v56, v61, s27, v60
	v_and_or_b32 v57, v63, s27, v62
	global_store_dwordx2 v[4:5], v[52:53], off offset:-1536
	global_store_dwordx2 v[4:5], v[54:55], off offset:-1024
	global_store_dwordx2 v[4:5], v[56:57], off offset:-512
	v_mov_b32_e32 v52, v2
	s_nop 1
	v_permlane32_swap_b32_e32 v52, v2
	v_bfe_u32 v49, v64, 16, 1
	v_bfe_u32 v51, v66, 16, 1
	v_bfe_u32 v50, v65, 16, 1
	v_add3_u32 v64, v64, v49, s26
	v_add3_u32 v66, v66, v51, s26
	v_bfe_u32 v54, v67, 16, 1
	v_add3_u32 v65, v65, v50, s26
	v_lshrrev_b32_e32 v64, 16, v64
	v_lshrrev_b32_e32 v53, 16, v66
	v_add3_u32 v54, v67, v54, s26
	v_and_or_b32 v58, v65, s27, v64
	v_and_or_b32 v59, v54, s27, v53
	global_store_dwordx2 v[4:5], v[58:59], off
	s_and_saveexec_b64 s[24:25], vcc
	s_cbranch_execz .Lx_B_latch
	s_waitcnt lgkmcnt(0)
	v_add_f32_e32 v2, v2, v52
	global_store_dword v3, v2, s[4:5]
	s_branch .Lx_B_latch
.Lx_B_latch:
	s_or_b64 exec, exec, s[24:25]
	s_add_i32 s29, s29, s30
	s_add_u32 s4, s4, s10
	s_addc_u32 s5, s5, s11
	v_lshl_add_u64 v[4:5], v[4:5], 0, s[14:15]
	s_cmpk_gt_i32 s29, 0x7fff
	v_mov_b32_e32 v6, v68
	v_mov_b32_e32 v7, v69
	s_cbranch_scc1 .LBB0_54
	s_branch .Lx_A

.LBB0_251:
	ds_read_b128 v[122:125], v245
	ds_read_b128 v[126:129], v245 offset:1024
	ds_read_b128 v[130:133], v245 offset:2048
	ds_read_b128 v[134:137], v245 offset:3072
	ds_read_b128 v[138:141], v246
	ds_read_b128 v[142:145], v246 offset:1024
	ds_read_b128 v[146:149], v246 offset:2048
	ds_read_b128 v[158:161], v246 offset:3072
	s_add_u32 s46, s44, 0x100
	s_addc_u32 s47, s45, 0
	s_cmp_eq_u32 s71, 40
	s_cselect_b32 s51, s9, s47
	s_cselect_b32 s50, s8, s46
	s_cselect_b32 s49, s43, s70
	s_cselect_b32 s48, s42, s69
	v_lshl_add_u64 v[210:211], s[44:45], 0, v[206:207]
	s_add_i32 m0, s53, 0xc000
	ds_read_b128 v[162:165], v247
	ds_read_b128 v[166:169], v247 offset:1024
	ds_read_b128 v[170:173], v247 offset:2048
	ds_read_b128 v[174:177], v247 offset:3072
	ds_read_b128 v[178:181], v247 offset:4096
	ds_read_b128 v[182:185], v247 offset:5120
	ds_read_b128 v[186:189], v247 offset:6144
	ds_read_b128 v[190:193], v247 offset:7168
	global_load_lds_dwordx4 v[210:211], off
	v_lshl_add_u64 v[210:211], s[44:45], 0, v[208:209]
	s_add_i32 m0, s53, 0xe000
	s_nop 0
	global_load_lds_dwordx4 v[210:211], off
	s_waitcnt vmcnt(8)
	s_waitcnt lgkmcnt(0)
	s_setprio 1
	s_barrier
	v_mfma_f32_16x16x32_bf16 v[154:157], v[122:125], v[162:165], v[154:157]
	v_mfma_f32_16x16x32_bf16 v[150:153], v[130:133], v[162:165], v[150:153]
	v_mfma_f32_16x16x32_bf16 v[110:113], v[122:125], v[170:173], v[110:113]
	v_mfma_f32_16x16x32_bf16 v[106:109], v[130:133], v[170:173], v[106:109]
	v_mfma_f32_16x16x32_bf16 v[94:97], v[122:125], v[178:181], v[94:97]
	v_mfma_f32_16x16x32_bf16 v[90:93], v[130:133], v[178:181], v[90:93]
	v_mfma_f32_16x16x32_bf16 v[78:81], v[122:125], v[186:189], v[78:81]
	v_mfma_f32_16x16x32_bf16 v[74:77], v[130:133], v[186:189], v[74:77]
	v_mfma_f32_16x16x32_bf16 v[154:157], v[126:129], v[166:169], v[154:157]
	v_mfma_f32_16x16x32_bf16 v[150:153], v[134:137], v[166:169], v[150:153]
	v_mfma_f32_16x16x32_bf16 v[110:113], v[126:129], v[174:177], v[110:113]
	v_mfma_f32_16x16x32_bf16 v[106:109], v[134:137], v[174:177], v[106:109]
	v_mfma_f32_16x16x32_bf16 v[94:97], v[126:129], v[182:185], v[94:97]
	v_mfma_f32_16x16x32_bf16 v[90:93], v[134:137], v[182:185], v[90:93]
	v_mfma_f32_16x16x32_bf16 v[78:81], v[126:129], v[190:193], v[78:81]
	v_mfma_f32_16x16x32_bf16 v[74:77], v[134:137], v[190:193], v[74:77]
	s_setprio 0
	s_setprio 1
	v_mfma_f32_16x16x32_bf16 v[118:121], v[138:141], v[162:165], v[118:121]
	v_mfma_f32_16x16x32_bf16 v[114:117], v[146:149], v[162:165], v[114:117]
	v_mfma_f32_16x16x32_bf16 v[102:105], v[138:141], v[170:173], v[102:105]
	v_mfma_f32_16x16x32_bf16 v[98:101], v[146:149], v[170:173], v[98:101]
	v_mfma_f32_16x16x32_bf16 v[86:89], v[138:141], v[178:181], v[86:89]
	v_mfma_f32_16x16x32_bf16 v[82:85], v[146:149], v[178:181], v[82:85]
	v_mfma_f32_16x16x32_bf16 v[70:73], v[138:141], v[186:189], v[70:73]
	v_mfma_f32_16x16x32_bf16 v[66:69], v[146:149], v[186:189], v[66:69]
	v_mfma_f32_16x16x32_bf16 v[118:121], v[142:145], v[166:169], v[118:121]
	v_mfma_f32_16x16x32_bf16 v[114:117], v[158:161], v[166:169], v[114:117]
	v_mfma_f32_16x16x32_bf16 v[102:105], v[142:145], v[174:177], v[102:105]
	v_mfma_f32_16x16x32_bf16 v[98:101], v[158:161], v[174:177], v[98:101]
	v_mfma_f32_16x16x32_bf16 v[86:89], v[142:145], v[182:185], v[86:89]
	v_mfma_f32_16x16x32_bf16 v[82:85], v[158:161], v[182:185], v[82:85]
	v_mfma_f32_16x16x32_bf16 v[70:73], v[142:145], v[190:193], v[70:73]
	v_mfma_f32_16x16x32_bf16 v[66:69], v[158:161], v[190:193], v[66:69]
	s_setprio 0
	s_barrier
	s_add_i32 s44, s63, s52
	v_lshl_add_u64 v[210:211], s[48:49], 0, v[196:197]
	s_mov_b32 m0, s44
	ds_read_b128 v[162:165], v247 offset:16384
	ds_read_b128 v[166:169], v247 offset:17408
	ds_read_b128 v[170:173], v247 offset:18432
	ds_read_b128 v[174:177], v247 offset:19456
	ds_read_b128 v[178:181], v247 offset:20480
	ds_read_b128 v[182:185], v247 offset:21504
	ds_read_b128 v[186:189], v247 offset:22528
	ds_read_b128 v[190:193], v247 offset:23552
	global_load_lds_dwordx4 v[210:211], off
	s_add_i32 m0, s44, 0x2000
	s_add_u32 s44, s48, 0xb0000
	v_lshl_add_u64 v[212:213], s[48:49], 0, v[200:201]
	s_addc_u32 s45, s49, 0
	s_add_i32 s72, s64, s52
	global_load_lds_dwordx4 v[212:213], off
	v_lshl_add_u64 v[214:215], s[44:45], 0, v[196:197]
	s_mov_b32 m0, s72
	v_lshl_add_u64 v[216:217], s[50:51], 0, v[198:199]
	global_load_lds_dwordx4 v[214:215], off
	v_lshl_add_u64 v[214:215], s[44:45], 0, v[200:201]
	s_add_i32 m0, s72, 0x2000
	s_nop 0
	global_load_lds_dwordx4 v[214:215], off
	v_lshl_add_u64 v[214:215], s[50:51], 0, v[194:195]
	s_mov_b32 m0, s53
	s_nop 0
	global_load_lds_dwordx4 v[214:215], off
	s_mov_b32 m0, s54
	s_nop 0
	global_load_lds_dwordx4 v[216:217], off
	s_waitcnt vmcnt(8)
	s_waitcnt lgkmcnt(0)
	s_setprio 1
	s_barrier
	v_mfma_f32_16x16x32_bf16 v[62:65], v[122:125], v[162:165], v[62:65]
	v_mfma_f32_16x16x32_bf16 v[58:61], v[130:133], v[162:165], v[58:61]
	v_mfma_f32_16x16x32_bf16 v[46:49], v[122:125], v[170:173], v[46:49]
	v_mfma_f32_16x16x32_bf16 v[42:45], v[130:133], v[170:173], v[42:45]
	v_mfma_f32_16x16x32_bf16 v[30:33], v[122:125], v[178:181], v[30:33]
	v_mfma_f32_16x16x32_bf16 v[26:29], v[130:133], v[178:181], v[26:29]
	v_mfma_f32_16x16x32_bf16 v[14:17], v[122:125], v[186:189], v[14:17]
	v_mfma_f32_16x16x32_bf16 v[10:13], v[130:133], v[186:189], v[10:13]
	v_mfma_f32_16x16x32_bf16 v[62:65], v[126:129], v[166:169], v[62:65]
	v_mfma_f32_16x16x32_bf16 v[58:61], v[134:137], v[166:169], v[58:61]
	v_mfma_f32_16x16x32_bf16 v[46:49], v[126:129], v[174:177], v[46:49]
	v_mfma_f32_16x16x32_bf16 v[42:45], v[134:137], v[174:177], v[42:45]
	v_mfma_f32_16x16x32_bf16 v[30:33], v[126:129], v[182:185], v[30:33]
	v_mfma_f32_16x16x32_bf16 v[26:29], v[134:137], v[182:185], v[26:29]
	v_mfma_f32_16x16x32_bf16 v[14:17], v[126:129], v[190:193], v[14:17]
	v_mfma_f32_16x16x32_bf16 v[10:13], v[134:137], v[190:193], v[10:13]
	s_setprio 0
	s_setprio 1
	v_mfma_f32_16x16x32_bf16 v[54:57], v[138:141], v[162:165], v[54:57]
	v_mfma_f32_16x16x32_bf16 v[50:53], v[146:149], v[162:165], v[50:53]
	v_mfma_f32_16x16x32_bf16 v[38:41], v[138:141], v[170:173], v[38:41]
	v_mfma_f32_16x16x32_bf16 v[34:37], v[146:149], v[170:173], v[34:37]
	v_mfma_f32_16x16x32_bf16 v[22:25], v[138:141], v[178:181], v[22:25]
	v_mfma_f32_16x16x32_bf16 v[18:21], v[146:149], v[178:181], v[18:21]
	v_mfma_f32_16x16x32_bf16 v[6:9], v[138:141], v[186:189], v[6:9]
	v_mfma_f32_16x16x32_bf16 v[2:5], v[146:149], v[186:189], v[2:5]
	v_mfma_f32_16x16x32_bf16 v[54:57], v[142:145], v[166:169], v[54:57]
	v_mfma_f32_16x16x32_bf16 v[50:53], v[158:161], v[166:169], v[50:53]
	v_mfma_f32_16x16x32_bf16 v[38:41], v[142:145], v[174:177], v[38:41]
	v_mfma_f32_16x16x32_bf16 v[34:37], v[158:161], v[174:177], v[34:37]
	v_mfma_f32_16x16x32_bf16 v[22:25], v[142:145], v[182:185], v[22:25]
	v_mfma_f32_16x16x32_bf16 v[18:21], v[158:161], v[182:185], v[18:21]
	v_mfma_f32_16x16x32_bf16 v[6:9], v[142:145], v[190:193], v[6:9]
	v_mfma_f32_16x16x32_bf16 v[2:5], v[158:161], v[190:193], v[2:5]
	s_setprio 0
	s_barrier
	s_add_i32 s72, 0, 0x18000
	s_add_i32 s73, 0, 0x1c000
	v_add_u32_e32 v134, s72, v244
	v_add_u32_e32 v158, s73, v244
	ds_read_b128 v[122:125], v134
	ds_read_b128 v[126:129], v134 offset:1024
	ds_read_b128 v[130:133], v134 offset:2048
	ds_read_b128 v[134:137], v134 offset:3072
	ds_read_b128 v[138:141], v158
	ds_read_b128 v[142:145], v158 offset:1024
	ds_read_b128 v[146:149], v158 offset:2048
	ds_read_b128 v[158:161], v158 offset:3072
	s_add_u32 s44, s50, 0xb0000
	s_addc_u32 s45, s51, 0
	s_mov_b32 m0, s55
	v_lshl_add_u64 v[218:219], s[44:45], 0, v[194:195]
	ds_read_b128 v[162:165], v247 offset:32768
	ds_read_b128 v[166:169], v247 offset:33792
	ds_read_b128 v[170:173], v247 offset:34816
	ds_read_b128 v[174:177], v247 offset:35840
	ds_read_b128 v[178:181], v247 offset:36864
	ds_read_b128 v[182:185], v247 offset:37888
	ds_read_b128 v[186:189], v247 offset:38912
	ds_read_b128 v[190:193], v247 offset:39936
	global_load_lds_dwordx4 v[218:219], off
	v_lshl_add_u64 v[218:219], s[44:45], 0, v[198:199]
	s_mov_b32 m0, s56
	s_nop 0
	global_load_lds_dwordx4 v[218:219], off
	s_waitcnt vmcnt(8)
	s_waitcnt lgkmcnt(0)
	s_setprio 1
	s_barrier
	v_mfma_f32_16x16x32_bf16 v[154:157], v[122:125], v[162:165], v[154:157]
	v_mfma_f32_16x16x32_bf16 v[150:153], v[130:133], v[162:165], v[150:153]
	v_mfma_f32_16x16x32_bf16 v[110:113], v[122:125], v[170:173], v[110:113]
	v_mfma_f32_16x16x32_bf16 v[106:109], v[130:133], v[170:173], v[106:109]
	v_mfma_f32_16x16x32_bf16 v[94:97], v[122:125], v[178:181], v[94:97]
	v_mfma_f32_16x16x32_bf16 v[90:93], v[130:133], v[178:181], v[90:93]
	v_mfma_f32_16x16x32_bf16 v[78:81], v[122:125], v[186:189], v[78:81]
	v_mfma_f32_16x16x32_bf16 v[74:77], v[130:133], v[186:189], v[74:77]
	v_mfma_f32_16x16x32_bf16 v[154:157], v[126:129], v[166:169], v[154:157]
	v_mfma_f32_16x16x32_bf16 v[150:153], v[134:137], v[166:169], v[150:153]
	v_mfma_f32_16x16x32_bf16 v[110:113], v[126:129], v[174:177], v[110:113]
	v_mfma_f32_16x16x32_bf16 v[106:109], v[134:137], v[174:177], v[106:109]
	v_mfma_f32_16x16x32_bf16 v[94:97], v[126:129], v[182:185], v[94:97]
	v_mfma_f32_16x16x32_bf16 v[90:93], v[134:137], v[182:185], v[90:93]
	v_mfma_f32_16x16x32_bf16 v[78:81], v[126:129], v[190:193], v[78:81]
	v_mfma_f32_16x16x32_bf16 v[74:77], v[134:137], v[190:193], v[74:77]
	s_setprio 0
	s_setprio 1
	v_mfma_f32_16x16x32_bf16 v[118:121], v[138:141], v[162:165], v[118:121]
	v_mfma_f32_16x16x32_bf16 v[114:117], v[146:149], v[162:165], v[114:117]
	v_mfma_f32_16x16x32_bf16 v[102:105], v[138:141], v[170:173], v[102:105]
	v_mfma_f32_16x16x32_bf16 v[98:101], v[146:149], v[170:173], v[98:101]
	v_mfma_f32_16x16x32_bf16 v[86:89], v[138:141], v[178:181], v[86:89]
	v_mfma_f32_16x16x32_bf16 v[82:85], v[146:149], v[178:181], v[82:85]
	v_mfma_f32_16x16x32_bf16 v[70:73], v[138:141], v[186:189], v[70:73]
	v_mfma_f32_16x16x32_bf16 v[66:69], v[146:149], v[186:189], v[66:69]
	v_mfma_f32_16x16x32_bf16 v[118:121], v[142:145], v[166:169], v[118:121]
	v_mfma_f32_16x16x32_bf16 v[114:117], v[158:161], v[166:169], v[114:117]
	v_mfma_f32_16x16x32_bf16 v[102:105], v[142:145], v[174:177], v[102:105]
	v_mfma_f32_16x16x32_bf16 v[98:101], v[158:161], v[174:177], v[98:101]
	v_mfma_f32_16x16x32_bf16 v[86:89], v[142:145], v[182:185], v[86:89]
	v_mfma_f32_16x16x32_bf16 v[82:85], v[158:161], v[182:185], v[82:85]
	v_mfma_f32_16x16x32_bf16 v[70:73], v[142:145], v[190:193], v[70:73]
	v_mfma_f32_16x16x32_bf16 v[66:69], v[158:161], v[190:193], v[66:69]
	s_setprio 0
	s_barrier
	s_add_i32 s44, s72, s52
	v_lshl_add_u64 v[210:211], v[210:211], 0, s[24:25]
	s_mov_b32 m0, s44
	ds_read_b128 v[162:165], v247 offset:49152
	ds_read_b128 v[166:169], v247 offset:50176
	ds_read_b128 v[170:173], v247 offset:51200
	ds_read_b128 v[174:177], v247 offset:52224
	ds_read_b128 v[178:181], v247 offset:53248
	ds_read_b128 v[182:185], v247 offset:54272
	ds_read_b128 v[186:189], v247 offset:55296
	ds_read_b128 v[190:193], v247 offset:56320
	global_load_lds_dwordx4 v[210:211], off
	s_add_i32 m0, s44, 0x2000
	s_add_u32 s44, s48, 0xb0080
	v_lshl_add_u64 v[210:211], v[212:213], 0, s[24:25]
	s_addc_u32 s45, s49, 0
	s_add_i32 s48, s73, s52
	global_load_lds_dwordx4 v[210:211], off
	v_lshl_add_u64 v[210:211], s[44:45], 0, v[196:197]
	s_mov_b32 m0, s48
	s_nop 0
	global_load_lds_dwordx4 v[210:211], off
	v_lshl_add_u64 v[210:211], s[44:45], 0, v[200:201]
	s_add_i32 m0, s48, 0x2000
	s_nop 0
	global_load_lds_dwordx4 v[210:211], off
	v_lshl_add_u64 v[210:211], v[214:215], 0, s[24:25]
	s_mov_b32 m0, s58
	s_nop 0
	global_load_lds_dwordx4 v[210:211], off
	v_lshl_add_u64 v[210:211], v[216:217], 0, s[24:25]
	s_mov_b32 m0, s59
	s_nop 0
	global_load_lds_dwordx4 v[210:211], off
	s_waitcnt vmcnt(8)
	s_waitcnt lgkmcnt(0)
	s_setprio 1
	s_barrier
	v_mfma_f32_16x16x32_bf16 v[62:65], v[122:125], v[162:165], v[62:65]
	v_mfma_f32_16x16x32_bf16 v[58:61], v[130:133], v[162:165], v[58:61]
	v_mfma_f32_16x16x32_bf16 v[46:49], v[122:125], v[170:173], v[46:49]
	v_mfma_f32_16x16x32_bf16 v[42:45], v[130:133], v[170:173], v[42:45]
	v_mfma_f32_16x16x32_bf16 v[30:33], v[122:125], v[178:181], v[30:33]
	v_mfma_f32_16x16x32_bf16 v[26:29], v[130:133], v[178:181], v[26:29]
	v_mfma_f32_16x16x32_bf16 v[14:17], v[122:125], v[186:189], v[14:17]
	v_mfma_f32_16x16x32_bf16 v[10:13], v[130:133], v[186:189], v[10:13]
	v_mfma_f32_16x16x32_bf16 v[62:65], v[126:129], v[166:169], v[62:65]
	v_mfma_f32_16x16x32_bf16 v[58:61], v[134:137], v[166:169], v[58:61]
	v_mfma_f32_16x16x32_bf16 v[46:49], v[126:129], v[174:177], v[46:49]
	v_mfma_f32_16x16x32_bf16 v[42:45], v[134:137], v[174:177], v[42:45]
	v_mfma_f32_16x16x32_bf16 v[30:33], v[126:129], v[182:185], v[30:33]
	v_mfma_f32_16x16x32_bf16 v[26:29], v[134:137], v[182:185], v[26:29]
	v_mfma_f32_16x16x32_bf16 v[14:17], v[126:129], v[190:193], v[14:17]
	v_mfma_f32_16x16x32_bf16 v[10:13], v[134:137], v[190:193], v[10:13]
	s_setprio 0
	s_setprio 1
	v_mfma_f32_16x16x32_bf16 v[54:57], v[138:141], v[162:165], v[54:57]
	v_mfma_f32_16x16x32_bf16 v[50:53], v[146:149], v[162:165], v[50:53]
	v_mfma_f32_16x16x32_bf16 v[38:41], v[138:141], v[170:173], v[38:41]
	v_mfma_f32_16x16x32_bf16 v[34:37], v[146:149], v[170:173], v[34:37]
	v_mfma_f32_16x16x32_bf16 v[22:25], v[138:141], v[178:181], v[22:25]
	v_mfma_f32_16x16x32_bf16 v[18:21], v[146:149], v[178:181], v[18:21]
	v_mfma_f32_16x16x32_bf16 v[6:9], v[138:141], v[186:189], v[6:9]
	v_mfma_f32_16x16x32_bf16 v[2:5], v[146:149], v[186:189], v[2:5]
	v_mfma_f32_16x16x32_bf16 v[54:57], v[142:145], v[166:169], v[54:57]
	v_mfma_f32_16x16x32_bf16 v[50:53], v[158:161], v[166:169], v[50:53]
	v_mfma_f32_16x16x32_bf16 v[38:41], v[142:145], v[174:177], v[38:41]
	v_mfma_f32_16x16x32_bf16 v[34:37], v[158:161], v[174:177], v[34:37]
	v_mfma_f32_16x16x32_bf16 v[22:25], v[142:145], v[182:185], v[22:25]
	v_mfma_f32_16x16x32_bf16 v[18:21], v[158:161], v[182:185], v[18:21]
	v_mfma_f32_16x16x32_bf16 v[6:9], v[142:145], v[190:193], v[6:9]
	v_mfma_f32_16x16x32_bf16 v[2:5], v[158:161], v[190:193], v[2:5]
	s_setprio 0
	s_barrier
	s_add_i32 s71, s71, 2
	s_add_u32 s69, s69, 0x100
	s_addc_u32 s70, s70, 0
	s_cmp_gt_u32 s71, 41
	s_mov_b64 s[44:45], s[46:47]
	s_cbranch_scc0 .LBB0_251
	s_lshl_b32 s44, s68, 8
	v_lshl_add_u32 v238, s67, 8, v243
	s_ashr_i32 s45, s44, 31
	s_lshl_b64 s[46:47], s[44:45], 1
	v_ashrrev_i32_e32 v239, 31, v238
	v_lshl_add_u64 v[126:127], v[204:205], 0, s[46:47]
	v_lshlrev_b64 v[240:241], 11, v[238:239]
	v_lshl_add_u64 v[122:123], v[126:127], 0, v[240:241]
	global_load_dwordx4 v[190:193], v[122:123], off
	global_load_dwordx4 v[186:189], v[122:123], off offset:256
	v_or_b32_e32 v234, 16, v238
	v_ashrrev_i32_e32 v235, 31, v234
	v_or_b32_e32 v230, 32, v238
	v_lshlrev_b64 v[236:237], 11, v[234:235]
	v_ashrrev_i32_e32 v231, 31, v230
	v_or_b32_e32 v226, 48, v238
	v_lshl_add_u64 v[122:123], v[126:127], 0, v[236:237]
	v_lshlrev_b64 v[232:233], 11, v[230:231]
	v_ashrrev_i32_e32 v227, 31, v226
	v_add_u32_e32 v222, 0x80, v238
	global_load_dwordx4 v[182:185], v[122:123], off
	global_load_dwordx4 v[178:181], v[122:123], off offset:256
	v_lshl_add_u64 v[122:123], v[126:127], 0, v[232:233]
	v_lshlrev_b64 v[228:229], 11, v[226:227]
	v_ashrrev_i32_e32 v223, 31, v222
	v_add_u32_e32 v218, 0x90, v238
	global_load_dwordx4 v[174:177], v[122:123], off
	global_load_dwordx4 v[170:173], v[122:123], off offset:256
	v_lshl_add_u64 v[122:123], v[126:127], 0, v[228:229]
	v_lshlrev_b64 v[224:225], 11, v[222:223]
	v_ashrrev_i32_e32 v219, 31, v218
	v_add_u32_e32 v212, 0xa0, v238
	v_add_u32_e32 v210, 0xb0, v238
	global_load_dwordx4 v[166:169], v[122:123], off
	global_load_dwordx4 v[162:165], v[122:123], off offset:256
	v_lshl_add_u64 v[122:123], v[126:127], 0, v[224:225]
	v_lshlrev_b64 v[220:221], 11, v[218:219]
	v_ashrrev_i32_e32 v213, 31, v212
	v_ashrrev_i32_e32 v211, 31, v210
	global_load_dwordx4 v[158:161], v[122:123], off
	global_load_dwordx4 v[146:149], v[122:123], off offset:256
	v_lshl_add_u64 v[122:123], v[126:127], 0, v[220:221]
	v_lshlrev_b64 v[216:217], 11, v[212:213]
	v_lshlrev_b64 v[214:215], 11, v[210:211]
	global_load_dwordx4 v[142:145], v[122:123], off
	global_load_dwordx4 v[138:141], v[122:123], off offset:256
	v_lshl_add_u64 v[122:123], v[126:127], 0, v[216:217]
	v_lshl_add_u64 v[126:127], v[126:127], 0, v[214:215]
	global_load_dwordx4 v[130:133], v[122:123], off
	s_nop 0
	global_load_dwordx4 v[122:125], v[122:123], off offset:256
	s_nop 0
	global_load_dwordx4 v[134:137], v[126:127], off
	s_nop 0
	global_load_dwordx4 v[126:129], v[126:127], off offset:256
	s_and_b64 vcc, exec, s[26:27]
	s_cbranch_vccz .LBB0_254
	s_barrier
.LBB0_254:
	v_lshl_add_u64 v[240:241], s[14:15], 0, v[240:241]
	v_lshl_add_u64 v[240:241], v[240:241], 0, s[46:47]
	v_lshl_add_u64 v[240:241], v[240:241], 0, v[202:203]
	v_and_b32_e32 v250, 64, v248
	v_xor_b32_e32 v249, 16, v248
	v_add_u32_e32 v250, 64, v250
	v_cmp_lt_i32_e32 vcc, v249, v250
	v_xor_b32_e32 v251, 32, v248
	s_waitcnt vmcnt(0)
	v_lshlrev_b32_e32 v252, 16, v190
	v_and_b32_e32 v253, 0xffff0000, v190
	v_lshlrev_b32_e32 v190, 16, v191
	v_and_b32_e32 v191, 0xffff0000, v191
	v_lshlrev_b32_e32 v254, 16, v192
	v_and_b32_e32 v255, 0xffff0000, v192
	v_lshlrev_b32_e32 v192, 16, v193
	v_and_b32_e32 v193, 0xffff0000, v193
	v_pk_fma_f32 v[156:157], v[156:157], 0.5, v[190:191] op_sel_hi:[1,0,1]
	v_pk_fma_f32 v[154:155], v[154:155], 0.5, v[252:253] op_sel_hi:[1,0,1]
	v_pk_fma_f32 v[190:191], v[152:153], 0.5, v[192:193] op_sel_hi:[1,0,1]
	v_pk_fma_f32 v[192:193], v[150:151], 0.5, v[254:255] op_sel_hi:[1,0,1]
	v_cvt_pk_bf16_f32 v150, v154, v155
	v_cvt_pk_bf16_f32 v151, v156, v157
	v_cvt_pk_bf16_f32 v152, v192, v193
	v_cvt_pk_bf16_f32 v153, v190, v191
	global_store_dwordx4 v[240:241], v[150:153], off
	v_cndmask_b32_e32 v249, v248, v249, vcc
	v_lshlrev_b32_e32 v249, 2, v249
	v_mul_f32_e32 v150, v155, v155
	v_mul_f32_e32 v151, v157, v157
	v_fmac_f32_e32 v150, v154, v154
	v_fmac_f32_e32 v151, v156, v156
	v_add_f32_e32 v150, v150, v151
	v_mul_f32_e32 v151, v193, v193
	v_mul_f32_e32 v152, v191, v191
	v_fmac_f32_e32 v151, v192, v192
	v_fmac_f32_e32 v152, v190, v190
	v_add_f32_e32 v151, v151, v152
	v_add_f32_e32 v190, v150, v151
	v_lshlrev_b32_e32 v150, 16, v186
	v_and_b32_e32 v151, 0xffff0000, v186
	v_lshlrev_b32_e32 v152, 16, v187
	v_and_b32_e32 v153, 0xffff0000, v187
	v_lshlrev_b32_e32 v154, 16, v188
	v_and_b32_e32 v155, 0xffff0000, v188
	v_lshlrev_b32_e32 v156, 16, v189
	v_and_b32_e32 v157, 0xffff0000, v189
	v_pk_fma_f32 v[120:121], v[120:121], 0.5, v[152:153] op_sel_hi:[1,0,1]
	v_pk_fma_f32 v[118:119], v[118:119], 0.5, v[150:151] op_sel_hi:[1,0,1]
	v_pk_fma_f32 v[150:151], v[116:117], 0.5, v[156:157] op_sel_hi:[1,0,1]
	v_pk_fma_f32 v[152:153], v[114:115], 0.5, v[154:155] op_sel_hi:[1,0,1]
	v_cvt_pk_bf16_f32 v114, v118, v119
	v_cvt_pk_bf16_f32 v115, v120, v121
	v_cvt_pk_bf16_f32 v116, v152, v153
	v_cvt_pk_bf16_f32 v117, v150, v151
	global_store_dwordx4 v[240:241], v[114:117], off offset:256
	v_cmp_lt_i32_e32 vcc, v251, v250
	s_nop 0
	v_mul_f32_e32 v114, v119, v119
	v_mul_f32_e32 v115, v121, v121
	v_fmac_f32_e32 v114, v118, v118
	v_fmac_f32_e32 v115, v120, v120
	v_add_f32_e32 v114, v114, v115
	v_mul_f32_e32 v115, v153, v153
	v_mul_f32_e32 v116, v151, v151
	v_fmac_f32_e32 v115, v152, v152
	v_fmac_f32_e32 v116, v150, v150
	v_add_f32_e32 v115, v115, v116
	v_add_f32_e32 v114, v114, v115
	v_add_f32_e32 v114, v190, v114
	v_mov_b32_e32 v115, v114
	s_nop 1
	v_permlane16_swap_b32_e32 v115, v114
	v_cndmask_b32_e32 v250, v248, v251, vcc
	v_lshlrev_b32_e32 v250, 2, v250
	s_waitcnt lgkmcnt(0)
	v_add_f32_e32 v114, v114, v115
	v_mov_b32_e32 v115, v114
	s_nop 1
	v_permlane32_swap_b32_e32 v115, v114
	s_and_saveexec_b64 s[46:47], s[4:5]
	s_cbranch_execz .LBB0_256
	v_lshl_add_u64 v[116:117], v[238:239], 2, s[16:17]
	s_waitcnt lgkmcnt(0)
	v_add_f32_e32 v114, v114, v115
	global_atomic_add_f32 v[116:117], v114, off

.LBB0_739:
	ds_read_b128 v[122:125], v245
	ds_read_b128 v[126:129], v245 offset:1024
	ds_read_b128 v[130:133], v245 offset:2048
	ds_read_b128 v[134:137], v245 offset:3072
	ds_read_b128 v[138:141], v246
	ds_read_b128 v[142:145], v246 offset:1024
	ds_read_b128 v[146:149], v246 offset:2048
	ds_read_b128 v[158:161], v246 offset:3072
	s_add_u32 s54, s52, 0xfffc0080
	s_addc_u32 s55, s53, -1
	s_cmp_eq_u32 s73, 12
	s_cselect_b32 s57, s43, s55
	s_cselect_b32 s56, s49, s54
	s_cselect_b32 s55, s27, s72
	s_cselect_b32 s54, s51, s71
	v_lshl_add_u64 v[210:211], s[52:53], 0, v[206:207]
	s_add_i32 m0, s59, 0xc000
	ds_read_b128 v[162:165], v247
	ds_read_b128 v[166:169], v247 offset:1024
	ds_read_b128 v[170:173], v247 offset:2048
	ds_read_b128 v[174:177], v247 offset:3072
	ds_read_b128 v[178:181], v247 offset:4096
	ds_read_b128 v[182:185], v247 offset:5120
	ds_read_b128 v[186:189], v247 offset:6144
	ds_read_b128 v[190:193], v247 offset:7168
	global_load_lds_dwordx4 v[210:211], off
	v_lshl_add_u64 v[210:211], s[52:53], 0, v[208:209]
	s_add_i32 m0, s59, 0xe000
	s_nop 0
	global_load_lds_dwordx4 v[210:211], off
	s_waitcnt vmcnt(8)
	s_waitcnt lgkmcnt(0)
	s_setprio 1
	s_barrier
	v_mfma_f32_16x16x32_bf16 v[154:157], v[122:125], v[162:165], v[154:157]
	v_mfma_f32_16x16x32_bf16 v[150:153], v[130:133], v[162:165], v[150:153]
	v_mfma_f32_16x16x32_bf16 v[110:113], v[122:125], v[170:173], v[110:113]
	v_mfma_f32_16x16x32_bf16 v[106:109], v[130:133], v[170:173], v[106:109]
	v_mfma_f32_16x16x32_bf16 v[94:97], v[122:125], v[178:181], v[94:97]
	v_mfma_f32_16x16x32_bf16 v[90:93], v[130:133], v[178:181], v[90:93]
	v_mfma_f32_16x16x32_bf16 v[78:81], v[122:125], v[186:189], v[78:81]
	v_mfma_f32_16x16x32_bf16 v[74:77], v[130:133], v[186:189], v[74:77]
	v_mfma_f32_16x16x32_bf16 v[154:157], v[126:129], v[166:169], v[154:157]
	v_mfma_f32_16x16x32_bf16 v[150:153], v[134:137], v[166:169], v[150:153]
	v_mfma_f32_16x16x32_bf16 v[110:113], v[126:129], v[174:177], v[110:113]
	v_mfma_f32_16x16x32_bf16 v[106:109], v[134:137], v[174:177], v[106:109]
	v_mfma_f32_16x16x32_bf16 v[94:97], v[126:129], v[182:185], v[94:97]
	v_mfma_f32_16x16x32_bf16 v[90:93], v[134:137], v[182:185], v[90:93]
	v_mfma_f32_16x16x32_bf16 v[78:81], v[126:129], v[190:193], v[78:81]
	v_mfma_f32_16x16x32_bf16 v[74:77], v[134:137], v[190:193], v[74:77]
	s_setprio 0
	s_setprio 1
	v_mfma_f32_16x16x32_bf16 v[118:121], v[138:141], v[162:165], v[118:121]
	v_mfma_f32_16x16x32_bf16 v[114:117], v[146:149], v[162:165], v[114:117]
	v_mfma_f32_16x16x32_bf16 v[102:105], v[138:141], v[170:173], v[102:105]
	v_mfma_f32_16x16x32_bf16 v[98:101], v[146:149], v[170:173], v[98:101]
	v_mfma_f32_16x16x32_bf16 v[86:89], v[138:141], v[178:181], v[86:89]
	v_mfma_f32_16x16x32_bf16 v[82:85], v[146:149], v[178:181], v[82:85]
	v_mfma_f32_16x16x32_bf16 v[70:73], v[138:141], v[186:189], v[70:73]
	v_mfma_f32_16x16x32_bf16 v[66:69], v[146:149], v[186:189], v[66:69]
	v_mfma_f32_16x16x32_bf16 v[118:121], v[142:145], v[166:169], v[118:121]
	v_mfma_f32_16x16x32_bf16 v[114:117], v[158:161], v[166:169], v[114:117]
	v_mfma_f32_16x16x32_bf16 v[102:105], v[142:145], v[174:177], v[102:105]
	v_mfma_f32_16x16x32_bf16 v[98:101], v[158:161], v[174:177], v[98:101]
	v_mfma_f32_16x16x32_bf16 v[86:89], v[142:145], v[182:185], v[86:89]
	v_mfma_f32_16x16x32_bf16 v[82:85], v[158:161], v[182:185], v[82:85]
	v_mfma_f32_16x16x32_bf16 v[70:73], v[142:145], v[190:193], v[70:73]
	v_mfma_f32_16x16x32_bf16 v[66:69], v[158:161], v[190:193], v[66:69]
	s_setprio 0
	s_barrier
	s_add_i32 s74, s69, s58
	v_lshl_add_u64 v[210:211], s[54:55], 0, v[196:197]
	s_mov_b32 m0, s74
	ds_read_b128 v[162:165], v247 offset:16384
	ds_read_b128 v[166:169], v247 offset:17408
	ds_read_b128 v[170:173], v247 offset:18432
	ds_read_b128 v[174:177], v247 offset:19456
	ds_read_b128 v[178:181], v247 offset:20480
	ds_read_b128 v[182:185], v247 offset:21504
	ds_read_b128 v[186:189], v247 offset:22528
	ds_read_b128 v[190:193], v247 offset:23552
	global_load_lds_dwordx4 v[210:211], off
	s_add_i32 m0, s74, 0x2000
	s_add_u32 s74, s54, 0x40000
	v_lshl_add_u64 v[212:213], s[54:55], 0, v[200:201]
	s_addc_u32 s75, s55, 0
	s_add_i32 s76, s70, s58
	global_load_lds_dwordx4 v[212:213], off
	v_lshl_add_u64 v[214:215], s[74:75], 0, v[196:197]
	s_mov_b32 m0, s76
	v_lshl_add_u64 v[216:217], s[56:57], 0, v[198:199]
	global_load_lds_dwordx4 v[214:215], off
	v_lshl_add_u64 v[214:215], s[74:75], 0, v[200:201]
	s_add_i32 m0, s76, 0x2000
	s_nop 0
	global_load_lds_dwordx4 v[214:215], off
	v_lshl_add_u64 v[214:215], s[56:57], 0, v[194:195]
	s_mov_b32 m0, s59
	s_nop 0
	global_load_lds_dwordx4 v[214:215], off
	s_mov_b32 m0, s60
	s_nop 0
	global_load_lds_dwordx4 v[216:217], off
	s_waitcnt vmcnt(8)
	s_waitcnt lgkmcnt(0)
	s_setprio 1
	s_barrier
	v_mfma_f32_16x16x32_bf16 v[62:65], v[122:125], v[162:165], v[62:65]
	v_mfma_f32_16x16x32_bf16 v[58:61], v[130:133], v[162:165], v[58:61]
	v_mfma_f32_16x16x32_bf16 v[46:49], v[122:125], v[170:173], v[46:49]
	v_mfma_f32_16x16x32_bf16 v[42:45], v[130:133], v[170:173], v[42:45]
	v_mfma_f32_16x16x32_bf16 v[30:33], v[122:125], v[178:181], v[30:33]
	v_mfma_f32_16x16x32_bf16 v[26:29], v[130:133], v[178:181], v[26:29]
	v_mfma_f32_16x16x32_bf16 v[14:17], v[122:125], v[186:189], v[14:17]
	v_mfma_f32_16x16x32_bf16 v[10:13], v[130:133], v[186:189], v[10:13]
	v_mfma_f32_16x16x32_bf16 v[62:65], v[126:129], v[166:169], v[62:65]
	v_mfma_f32_16x16x32_bf16 v[58:61], v[134:137], v[166:169], v[58:61]
	v_mfma_f32_16x16x32_bf16 v[46:49], v[126:129], v[174:177], v[46:49]
	v_mfma_f32_16x16x32_bf16 v[42:45], v[134:137], v[174:177], v[42:45]
	v_mfma_f32_16x16x32_bf16 v[30:33], v[126:129], v[182:185], v[30:33]
	v_mfma_f32_16x16x32_bf16 v[26:29], v[134:137], v[182:185], v[26:29]
	v_mfma_f32_16x16x32_bf16 v[14:17], v[126:129], v[190:193], v[14:17]
	v_mfma_f32_16x16x32_bf16 v[10:13], v[134:137], v[190:193], v[10:13]
	s_setprio 0
	s_setprio 1
	v_mfma_f32_16x16x32_bf16 v[54:57], v[138:141], v[162:165], v[54:57]
	v_mfma_f32_16x16x32_bf16 v[50:53], v[146:149], v[162:165], v[50:53]
	v_mfma_f32_16x16x32_bf16 v[38:41], v[138:141], v[170:173], v[38:41]
	v_mfma_f32_16x16x32_bf16 v[34:37], v[146:149], v[170:173], v[34:37]
	v_mfma_f32_16x16x32_bf16 v[22:25], v[138:141], v[178:181], v[22:25]
	v_mfma_f32_16x16x32_bf16 v[18:21], v[146:149], v[178:181], v[18:21]
	v_mfma_f32_16x16x32_bf16 v[6:9], v[138:141], v[186:189], v[6:9]
	v_mfma_f32_16x16x32_bf16 v[2:5], v[146:149], v[186:189], v[2:5]
	v_mfma_f32_16x16x32_bf16 v[54:57], v[142:145], v[166:169], v[54:57]
	v_mfma_f32_16x16x32_bf16 v[50:53], v[158:161], v[166:169], v[50:53]
	v_mfma_f32_16x16x32_bf16 v[38:41], v[142:145], v[174:177], v[38:41]
	v_mfma_f32_16x16x32_bf16 v[34:37], v[158:161], v[174:177], v[34:37]
	v_mfma_f32_16x16x32_bf16 v[22:25], v[142:145], v[182:185], v[22:25]
	v_mfma_f32_16x16x32_bf16 v[18:21], v[158:161], v[182:185], v[18:21]
	v_mfma_f32_16x16x32_bf16 v[6:9], v[142:145], v[190:193], v[6:9]
	v_mfma_f32_16x16x32_bf16 v[2:5], v[158:161], v[190:193], v[2:5]
	s_setprio 0
	s_barrier
	s_add_i32 s74, 0, 0x18000
	s_add_i32 s75, 0, 0x1c000
	v_add_u32_e32 v134, s74, v244
	v_add_u32_e32 v158, s75, v244
	ds_read_b128 v[122:125], v134
	ds_read_b128 v[126:129], v134 offset:1024
	ds_read_b128 v[130:133], v134 offset:2048
	ds_read_b128 v[134:137], v134 offset:3072
	ds_read_b128 v[138:141], v158
	ds_read_b128 v[142:145], v158 offset:1024
	ds_read_b128 v[146:149], v158 offset:2048
	ds_read_b128 v[158:161], v158 offset:3072
	s_add_u32 s56, s56, 0x40000
	s_addc_u32 s57, s57, 0
	s_mov_b32 m0, s61
	v_lshl_add_u64 v[218:219], s[56:57], 0, v[194:195]
	ds_read_b128 v[162:165], v247 offset:32768
	ds_read_b128 v[166:169], v247 offset:33792
	ds_read_b128 v[170:173], v247 offset:34816
	ds_read_b128 v[174:177], v247 offset:35840
	ds_read_b128 v[178:181], v247 offset:36864
	ds_read_b128 v[182:185], v247 offset:37888
	ds_read_b128 v[186:189], v247 offset:38912
	ds_read_b128 v[190:193], v247 offset:39936
	global_load_lds_dwordx4 v[218:219], off
	v_lshl_add_u64 v[218:219], s[56:57], 0, v[198:199]
	s_mov_b32 m0, s62
	s_nop 0
	global_load_lds_dwordx4 v[218:219], off
	s_waitcnt vmcnt(8)
	s_waitcnt lgkmcnt(0)
	s_setprio 1
	s_barrier
	v_mfma_f32_16x16x32_bf16 v[154:157], v[122:125], v[162:165], v[154:157]
	v_mfma_f32_16x16x32_bf16 v[150:153], v[130:133], v[162:165], v[150:153]
	v_mfma_f32_16x16x32_bf16 v[110:113], v[122:125], v[170:173], v[110:113]
	v_mfma_f32_16x16x32_bf16 v[106:109], v[130:133], v[170:173], v[106:109]
	v_mfma_f32_16x16x32_bf16 v[94:97], v[122:125], v[178:181], v[94:97]
	v_mfma_f32_16x16x32_bf16 v[90:93], v[130:133], v[178:181], v[90:93]
	v_mfma_f32_16x16x32_bf16 v[78:81], v[122:125], v[186:189], v[78:81]
	v_mfma_f32_16x16x32_bf16 v[74:77], v[130:133], v[186:189], v[74:77]
	v_mfma_f32_16x16x32_bf16 v[154:157], v[126:129], v[166:169], v[154:157]
	v_mfma_f32_16x16x32_bf16 v[150:153], v[134:137], v[166:169], v[150:153]
	v_mfma_f32_16x16x32_bf16 v[110:113], v[126:129], v[174:177], v[110:113]
	v_mfma_f32_16x16x32_bf16 v[106:109], v[134:137], v[174:177], v[106:109]
	v_mfma_f32_16x16x32_bf16 v[94:97], v[126:129], v[182:185], v[94:97]
	v_mfma_f32_16x16x32_bf16 v[90:93], v[134:137], v[182:185], v[90:93]
	v_mfma_f32_16x16x32_bf16 v[78:81], v[126:129], v[190:193], v[78:81]
	v_mfma_f32_16x16x32_bf16 v[74:77], v[134:137], v[190:193], v[74:77]
	s_setprio 0
	s_setprio 1
	v_mfma_f32_16x16x32_bf16 v[118:121], v[138:141], v[162:165], v[118:121]
	v_mfma_f32_16x16x32_bf16 v[114:117], v[146:149], v[162:165], v[114:117]
	v_mfma_f32_16x16x32_bf16 v[102:105], v[138:141], v[170:173], v[102:105]
	v_mfma_f32_16x16x32_bf16 v[98:101], v[146:149], v[170:173], v[98:101]
	v_mfma_f32_16x16x32_bf16 v[86:89], v[138:141], v[178:181], v[86:89]
	v_mfma_f32_16x16x32_bf16 v[82:85], v[146:149], v[178:181], v[82:85]
	v_mfma_f32_16x16x32_bf16 v[70:73], v[138:141], v[186:189], v[70:73]
	v_mfma_f32_16x16x32_bf16 v[66:69], v[146:149], v[186:189], v[66:69]
	v_mfma_f32_16x16x32_bf16 v[118:121], v[142:145], v[166:169], v[118:121]
	v_mfma_f32_16x16x32_bf16 v[114:117], v[158:161], v[166:169], v[114:117]
	v_mfma_f32_16x16x32_bf16 v[102:105], v[142:145], v[174:177], v[102:105]
	v_mfma_f32_16x16x32_bf16 v[98:101], v[158:161], v[174:177], v[98:101]
	v_mfma_f32_16x16x32_bf16 v[86:89], v[142:145], v[182:185], v[86:89]
	v_mfma_f32_16x16x32_bf16 v[82:85], v[158:161], v[182:185], v[82:85]
	v_mfma_f32_16x16x32_bf16 v[70:73], v[142:145], v[190:193], v[70:73]
	v_mfma_f32_16x16x32_bf16 v[66:69], v[158:161], v[190:193], v[66:69]
	s_setprio 0
	s_barrier
	s_add_i32 s56, s74, s58
	v_lshl_add_u64 v[210:211], v[210:211], 0, s[16:17]
	s_mov_b32 m0, s56
	ds_read_b128 v[162:165], v247 offset:49152
	ds_read_b128 v[166:169], v247 offset:50176
	ds_read_b128 v[170:173], v247 offset:51200
	ds_read_b128 v[174:177], v247 offset:52224
	ds_read_b128 v[178:181], v247 offset:53248
	ds_read_b128 v[182:185], v247 offset:54272
	ds_read_b128 v[186:189], v247 offset:55296
	ds_read_b128 v[190:193], v247 offset:56320
	global_load_lds_dwordx4 v[210:211], off
	s_add_i32 m0, s56, 0x2000
	s_add_u32 s54, s54, 0x40080
	v_lshl_add_u64 v[210:211], v[212:213], 0, s[16:17]
	s_addc_u32 s55, s55, 0
	s_add_i32 s56, s75, s58
	global_load_lds_dwordx4 v[210:211], off
	v_lshl_add_u64 v[210:211], s[54:55], 0, v[196:197]
	s_mov_b32 m0, s56
	s_nop 0
	global_load_lds_dwordx4 v[210:211], off
	v_lshl_add_u64 v[210:211], s[54:55], 0, v[200:201]
	s_add_i32 m0, s56, 0x2000
	s_nop 0
	global_load_lds_dwordx4 v[210:211], off
	v_lshl_add_u64 v[210:211], v[214:215], 0, s[16:17]
	s_mov_b32 m0, s64
	s_nop 0
	global_load_lds_dwordx4 v[210:211], off
	v_lshl_add_u64 v[210:211], v[216:217], 0, s[16:17]
	s_mov_b32 m0, s65
	s_nop 0
	global_load_lds_dwordx4 v[210:211], off
	s_waitcnt vmcnt(8)
	s_waitcnt lgkmcnt(0)
	s_setprio 1
	s_barrier
	v_mfma_f32_16x16x32_bf16 v[62:65], v[122:125], v[162:165], v[62:65]
	v_mfma_f32_16x16x32_bf16 v[58:61], v[130:133], v[162:165], v[58:61]
	v_mfma_f32_16x16x32_bf16 v[46:49], v[122:125], v[170:173], v[46:49]
	v_mfma_f32_16x16x32_bf16 v[42:45], v[130:133], v[170:173], v[42:45]
	v_mfma_f32_16x16x32_bf16 v[30:33], v[122:125], v[178:181], v[30:33]
	v_mfma_f32_16x16x32_bf16 v[26:29], v[130:133], v[178:181], v[26:29]
	v_mfma_f32_16x16x32_bf16 v[14:17], v[122:125], v[186:189], v[14:17]
	v_mfma_f32_16x16x32_bf16 v[10:13], v[130:133], v[186:189], v[10:13]
	v_mfma_f32_16x16x32_bf16 v[62:65], v[126:129], v[166:169], v[62:65]
	v_mfma_f32_16x16x32_bf16 v[58:61], v[134:137], v[166:169], v[58:61]
	v_mfma_f32_16x16x32_bf16 v[46:49], v[126:129], v[174:177], v[46:49]
	v_mfma_f32_16x16x32_bf16 v[42:45], v[134:137], v[174:177], v[42:45]
	v_mfma_f32_16x16x32_bf16 v[30:33], v[126:129], v[182:185], v[30:33]
	v_mfma_f32_16x16x32_bf16 v[26:29], v[134:137], v[182:185], v[26:29]
	v_mfma_f32_16x16x32_bf16 v[14:17], v[126:129], v[190:193], v[14:17]
	v_mfma_f32_16x16x32_bf16 v[10:13], v[134:137], v[190:193], v[10:13]
	s_setprio 0
	s_setprio 1
	v_mfma_f32_16x16x32_bf16 v[54:57], v[138:141], v[162:165], v[54:57]
	v_mfma_f32_16x16x32_bf16 v[50:53], v[146:149], v[162:165], v[50:53]
	v_mfma_f32_16x16x32_bf16 v[38:41], v[138:141], v[170:173], v[38:41]
	v_mfma_f32_16x16x32_bf16 v[34:37], v[146:149], v[170:173], v[34:37]
	v_mfma_f32_16x16x32_bf16 v[22:25], v[138:141], v[178:181], v[22:25]
	v_mfma_f32_16x16x32_bf16 v[18:21], v[146:149], v[178:181], v[18:21]
	v_mfma_f32_16x16x32_bf16 v[6:9], v[138:141], v[186:189], v[6:9]
	v_mfma_f32_16x16x32_bf16 v[2:5], v[146:149], v[186:189], v[2:5]
	v_mfma_f32_16x16x32_bf16 v[54:57], v[142:145], v[166:169], v[54:57]
	v_mfma_f32_16x16x32_bf16 v[50:53], v[158:161], v[166:169], v[50:53]
	v_mfma_f32_16x16x32_bf16 v[38:41], v[142:145], v[174:177], v[38:41]
	v_mfma_f32_16x16x32_bf16 v[34:37], v[158:161], v[174:177], v[34:37]
	v_mfma_f32_16x16x32_bf16 v[22:25], v[142:145], v[182:185], v[22:25]
	v_mfma_f32_16x16x32_bf16 v[18:21], v[158:161], v[182:185], v[18:21]
	v_mfma_f32_16x16x32_bf16 v[6:9], v[142:145], v[190:193], v[6:9]
	v_mfma_f32_16x16x32_bf16 v[2:5], v[158:161], v[190:193], v[2:5]
	s_setprio 0
	s_barrier
	s_add_i32 s73, s73, 2
	s_add_u32 s52, s52, 0x100
	s_addc_u32 s53, s53, 0
	s_add_u32 s71, s71, 0x100
	s_addc_u32 s72, s72, 0
	s_cmp_gt_u32 s73, 13
	s_cbranch_scc0 .LBB0_739
	v_lshl_add_u32 v238, s48, 8, v243
	s_lshl_b32 s48, s50, 8
	s_ashr_i32 s49, s48, 31
	s_lshl_b64 s[50:51], s[48:49], 1
	v_ashrrev_i32_e32 v239, 31, v238
	v_lshl_add_u64 v[126:127], v[204:205], 0, s[50:51]
	v_lshlrev_b64 v[240:241], 11, v[238:239]
	v_lshl_add_u64 v[122:123], v[126:127], 0, v[240:241]
	global_load_dwordx4 v[190:193], v[122:123], off
	global_load_dwordx4 v[186:189], v[122:123], off offset:256
	v_or_b32_e32 v234, 16, v238
	v_ashrrev_i32_e32 v235, 31, v234
	v_or_b32_e32 v230, 32, v238
	v_lshlrev_b64 v[236:237], 11, v[234:235]
	v_ashrrev_i32_e32 v231, 31, v230
	v_or_b32_e32 v226, 48, v238
	v_lshl_add_u64 v[122:123], v[126:127], 0, v[236:237]
	v_lshlrev_b64 v[232:233], 11, v[230:231]
	v_ashrrev_i32_e32 v227, 31, v226
	v_add_u32_e32 v222, 0x80, v238
	global_load_dwordx4 v[182:185], v[122:123], off
	global_load_dwordx4 v[178:181], v[122:123], off offset:256
	v_lshl_add_u64 v[122:123], v[126:127], 0, v[232:233]
	v_lshlrev_b64 v[228:229], 11, v[226:227]
	v_ashrrev_i32_e32 v223, 31, v222
	v_add_u32_e32 v218, 0x90, v238
	global_load_dwordx4 v[174:177], v[122:123], off
	global_load_dwordx4 v[170:173], v[122:123], off offset:256
	v_lshl_add_u64 v[122:123], v[126:127], 0, v[228:229]
	v_lshlrev_b64 v[224:225], 11, v[222:223]
	v_ashrrev_i32_e32 v219, 31, v218
	v_add_u32_e32 v212, 0xa0, v238
	v_add_u32_e32 v210, 0xb0, v238
	global_load_dwordx4 v[166:169], v[122:123], off
	global_load_dwordx4 v[162:165], v[122:123], off offset:256
	v_lshl_add_u64 v[122:123], v[126:127], 0, v[224:225]
	v_lshlrev_b64 v[220:221], 11, v[218:219]
	v_ashrrev_i32_e32 v213, 31, v212
	v_ashrrev_i32_e32 v211, 31, v210
	global_load_dwordx4 v[158:161], v[122:123], off
	global_load_dwordx4 v[146:149], v[122:123], off offset:256
	v_lshl_add_u64 v[122:123], v[126:127], 0, v[220:221]
	v_lshlrev_b64 v[216:217], 11, v[212:213]
	v_lshlrev_b64 v[214:215], 11, v[210:211]
	global_load_dwordx4 v[142:145], v[122:123], off
	global_load_dwordx4 v[138:141], v[122:123], off offset:256
	v_lshl_add_u64 v[122:123], v[126:127], 0, v[216:217]
	v_lshl_add_u64 v[126:127], v[126:127], 0, v[214:215]
	global_load_dwordx4 v[130:133], v[122:123], off
	s_nop 0
	global_load_dwordx4 v[122:125], v[122:123], off offset:256
	s_nop 0
	global_load_dwordx4 v[134:137], v[126:127], off
	s_nop 0
	global_load_dwordx4 v[126:129], v[126:127], off offset:256
	s_and_b64 vcc, exec, s[24:25]
	s_cbranch_vccz .LBB0_742
	s_barrier
.LBB0_742:
	v_lshl_add_u64 v[240:241], s[12:13], 0, v[240:241]
	v_lshl_add_u64 v[240:241], v[240:241], 0, s[50:51]
	v_lshl_add_u64 v[240:241], v[240:241], 0, v[202:203]
	v_and_b32_e32 v250, 64, v248
	v_xor_b32_e32 v249, 16, v248
	v_add_u32_e32 v250, 64, v250
	v_cmp_lt_i32_e32 vcc, v249, v250
	v_xor_b32_e32 v251, 32, v248
	s_waitcnt vmcnt(0)
	v_lshlrev_b32_e32 v252, 16, v190
	v_and_b32_e32 v253, 0xffff0000, v190
	v_lshlrev_b32_e32 v190, 16, v191
	v_and_b32_e32 v191, 0xffff0000, v191
	v_lshlrev_b32_e32 v254, 16, v192
	v_and_b32_e32 v255, 0xffff0000, v192
	v_lshlrev_b32_e32 v192, 16, v193
	v_and_b32_e32 v193, 0xffff0000, v193
	v_pk_add_f32 v[156:157], v[156:157], v[190:191]
	v_pk_add_f32 v[154:155], v[154:155], v[252:253]
	v_pk_add_f32 v[190:191], v[152:153], v[192:193]
	v_pk_add_f32 v[192:193], v[150:151], v[254:255]
	v_cvt_pk_bf16_f32 v150, v154, v155
	v_cvt_pk_bf16_f32 v151, v156, v157
	v_cvt_pk_bf16_f32 v152, v192, v193
	v_cvt_pk_bf16_f32 v153, v190, v191
	global_store_dwordx4 v[240:241], v[150:153], off
	v_cndmask_b32_e32 v249, v248, v249, vcc
	v_lshlrev_b32_e32 v249, 2, v249
	v_mul_f32_e32 v150, v155, v155
	v_mul_f32_e32 v151, v157, v157
	v_fmac_f32_e32 v150, v154, v154
	v_fmac_f32_e32 v151, v156, v156
	v_add_f32_e32 v150, v150, v151
	v_mul_f32_e32 v151, v193, v193
	v_mul_f32_e32 v152, v191, v191
	v_fmac_f32_e32 v151, v192, v192
	v_fmac_f32_e32 v152, v190, v190
	v_add_f32_e32 v151, v151, v152
	v_add_f32_e32 v190, v150, v151
	v_lshlrev_b32_e32 v150, 16, v186
	v_and_b32_e32 v151, 0xffff0000, v186
	v_lshlrev_b32_e32 v152, 16, v187
	v_and_b32_e32 v153, 0xffff0000, v187
	v_lshlrev_b32_e32 v154, 16, v188
	v_and_b32_e32 v155, 0xffff0000, v188
	v_lshlrev_b32_e32 v156, 16, v189
	v_and_b32_e32 v157, 0xffff0000, v189
	v_pk_add_f32 v[120:121], v[120:121], v[152:153]
	v_pk_add_f32 v[118:119], v[118:119], v[150:151]
	v_pk_add_f32 v[150:151], v[116:117], v[156:157]
	v_pk_add_f32 v[152:153], v[114:115], v[154:155]
	v_cvt_pk_bf16_f32 v114, v118, v119
	v_cvt_pk_bf16_f32 v115, v120, v121
	v_cvt_pk_bf16_f32 v116, v152, v153
	v_cvt_pk_bf16_f32 v117, v150, v151
	global_store_dwordx4 v[240:241], v[114:117], off offset:256
	v_cmp_lt_i32_e32 vcc, v251, v250
	s_nop 0
	v_mul_f32_e32 v114, v119, v119
	v_mul_f32_e32 v115, v121, v121
	v_fmac_f32_e32 v114, v118, v118
	v_fmac_f32_e32 v115, v120, v120
	v_add_f32_e32 v114, v114, v115
	v_mul_f32_e32 v115, v153, v153
	v_mul_f32_e32 v116, v151, v151
	v_fmac_f32_e32 v115, v152, v152
	v_fmac_f32_e32 v116, v150, v150
	v_add_f32_e32 v115, v115, v116
	v_add_f32_e32 v114, v114, v115
	v_add_f32_e32 v114, v190, v114
	v_mov_b32_e32 v115, v114
	s_nop 1
	v_permlane16_swap_b32_e32 v115, v114
	v_cndmask_b32_e32 v250, v248, v251, vcc
	v_lshlrev_b32_e32 v250, 2, v250
	s_waitcnt lgkmcnt(0)
	v_add_f32_e32 v114, v114, v115
	v_mov_b32_e32 v115, v114
	s_nop 1
	v_permlane32_swap_b32_e32 v115, v114
	s_and_saveexec_b64 s[50:51], s[4:5]
	s_cbranch_execz .LBB0_744
	v_lshl_add_u64 v[116:117], v[238:239], 2, s[14:15]
	s_waitcnt lgkmcnt(0)
	v_add_f32_e32 v114, v114, v115
	global_atomic_add_f32 v[116:117], v114, off

.LBB0_1909:
	ds_read_b128 v[114:117], v225
	ds_read_b128 v[126:129], v225 offset:1024
	ds_read_b128 v[138:141], v225 offset:2048
	ds_read_b128 v[142:145], v225 offset:3072
	ds_read_b128 v[146:149], v226
	ds_read_b128 v[150:153], v226 offset:1024
	ds_read_b128 v[154:157], v226 offset:2048
	ds_read_b128 v[158:161], v226 offset:3072
	s_add_u32 s46, s44, 0x100
	s_addc_u32 s47, s45, 0
	s_cmp_eq_u32 s71, 40
	s_cselect_b32 s51, s9, s47
	s_cselect_b32 s50, s8, s46
	s_cselect_b32 s49, s43, s70
	s_cselect_b32 s48, s42, s69
	v_lshl_add_u64 v[214:215], s[44:45], 0, v[198:199]
	s_add_i32 m0, s53, 0xc000
	ds_read_b128 v[162:165], v227
	ds_read_b128 v[166:169], v227 offset:1024
	ds_read_b128 v[170:173], v227 offset:2048
	ds_read_b128 v[174:177], v227 offset:3072
	ds_read_b128 v[178:181], v227 offset:4096
	ds_read_b128 v[182:185], v227 offset:5120
	ds_read_b128 v[206:209], v227 offset:6144
	ds_read_b128 v[210:213], v227 offset:7168
	global_load_lds_dwordx4 v[214:215], off
	v_lshl_add_u64 v[214:215], s[44:45], 0, v[200:201]
	s_add_i32 m0, s53, 0xe000
	s_nop 0
	global_load_lds_dwordx4 v[214:215], off
	s_waitcnt vmcnt(8)
	s_waitcnt lgkmcnt(0)
	s_setprio 1
	s_barrier
	v_mfma_f32_16x16x32_bf16 v[134:137], v[114:117], v[162:165], v[134:137]
	v_mfma_f32_16x16x32_bf16 v[130:133], v[138:141], v[162:165], v[130:133]
	v_mfma_f32_16x16x32_bf16 v[110:113], v[114:117], v[170:173], v[110:113]
	v_mfma_f32_16x16x32_bf16 v[106:109], v[138:141], v[170:173], v[106:109]
	v_mfma_f32_16x16x32_bf16 v[94:97], v[114:117], v[178:181], v[94:97]
	v_mfma_f32_16x16x32_bf16 v[90:93], v[138:141], v[178:181], v[90:93]
	v_mfma_f32_16x16x32_bf16 v[78:81], v[114:117], v[206:209], v[78:81]
	v_mfma_f32_16x16x32_bf16 v[74:77], v[138:141], v[206:209], v[74:77]
	v_mfma_f32_16x16x32_bf16 v[134:137], v[126:129], v[166:169], v[134:137]
	v_mfma_f32_16x16x32_bf16 v[130:133], v[142:145], v[166:169], v[130:133]
	v_mfma_f32_16x16x32_bf16 v[110:113], v[126:129], v[174:177], v[110:113]
	v_mfma_f32_16x16x32_bf16 v[106:109], v[142:145], v[174:177], v[106:109]
	v_mfma_f32_16x16x32_bf16 v[94:97], v[126:129], v[182:185], v[94:97]
	v_mfma_f32_16x16x32_bf16 v[90:93], v[142:145], v[182:185], v[90:93]
	v_mfma_f32_16x16x32_bf16 v[78:81], v[126:129], v[210:213], v[78:81]
	v_mfma_f32_16x16x32_bf16 v[74:77], v[142:145], v[210:213], v[74:77]
	s_setprio 0
	s_setprio 1
	v_mfma_f32_16x16x32_bf16 v[122:125], v[146:149], v[162:165], v[122:125]
	v_mfma_f32_16x16x32_bf16 v[118:121], v[154:157], v[162:165], v[118:121]
	v_mfma_f32_16x16x32_bf16 v[102:105], v[146:149], v[170:173], v[102:105]
	v_mfma_f32_16x16x32_bf16 v[98:101], v[154:157], v[170:173], v[98:101]
	v_mfma_f32_16x16x32_bf16 v[86:89], v[146:149], v[178:181], v[86:89]
	v_mfma_f32_16x16x32_bf16 v[82:85], v[154:157], v[178:181], v[82:85]
	v_mfma_f32_16x16x32_bf16 v[70:73], v[146:149], v[206:209], v[70:73]
	v_mfma_f32_16x16x32_bf16 v[66:69], v[154:157], v[206:209], v[66:69]
	v_mfma_f32_16x16x32_bf16 v[122:125], v[150:153], v[166:169], v[122:125]
	v_mfma_f32_16x16x32_bf16 v[118:121], v[158:161], v[166:169], v[118:121]
	v_mfma_f32_16x16x32_bf16 v[102:105], v[150:153], v[174:177], v[102:105]
	v_mfma_f32_16x16x32_bf16 v[98:101], v[158:161], v[174:177], v[98:101]
	v_mfma_f32_16x16x32_bf16 v[86:89], v[150:153], v[182:185], v[86:89]
	v_mfma_f32_16x16x32_bf16 v[82:85], v[158:161], v[182:185], v[82:85]
	v_mfma_f32_16x16x32_bf16 v[70:73], v[150:153], v[210:213], v[70:73]
	v_mfma_f32_16x16x32_bf16 v[66:69], v[158:161], v[210:213], v[66:69]
	s_setprio 0
	s_barrier
	s_add_i32 s44, s63, s52
	v_lshl_add_u64 v[214:215], s[48:49], 0, v[188:189]
	s_mov_b32 m0, s44
	ds_read_b128 v[162:165], v227 offset:16384
	ds_read_b128 v[166:169], v227 offset:17408
	ds_read_b128 v[170:173], v227 offset:18432
	ds_read_b128 v[174:177], v227 offset:19456
	ds_read_b128 v[178:181], v227 offset:20480
	ds_read_b128 v[182:185], v227 offset:21504
	ds_read_b128 v[206:209], v227 offset:22528
	ds_read_b128 v[210:213], v227 offset:23552
	global_load_lds_dwordx4 v[214:215], off
	s_add_i32 m0, s44, 0x2000
	s_add_u32 s44, s48, 0xb0000
	v_lshl_add_u64 v[216:217], s[48:49], 0, v[192:193]
	s_addc_u32 s45, s49, 0
	s_add_i32 s72, s64, s52
	global_load_lds_dwordx4 v[216:217], off
	v_lshl_add_u64 v[218:219], s[44:45], 0, v[188:189]
	s_mov_b32 m0, s72
	v_lshl_add_u64 v[220:221], s[50:51], 0, v[190:191]
	global_load_lds_dwordx4 v[218:219], off
	v_lshl_add_u64 v[218:219], s[44:45], 0, v[192:193]
	s_add_i32 m0, s72, 0x2000
	s_nop 0
	global_load_lds_dwordx4 v[218:219], off
	v_lshl_add_u64 v[218:219], s[50:51], 0, v[186:187]
	s_mov_b32 m0, s53
	s_nop 0
	global_load_lds_dwordx4 v[218:219], off
	s_mov_b32 m0, s54
	s_nop 0
	global_load_lds_dwordx4 v[220:221], off
	s_waitcnt vmcnt(8)
	s_waitcnt lgkmcnt(0)
	s_setprio 1
	s_barrier
	v_mfma_f32_16x16x32_bf16 v[62:65], v[114:117], v[162:165], v[62:65]
	v_mfma_f32_16x16x32_bf16 v[58:61], v[138:141], v[162:165], v[58:61]
	v_mfma_f32_16x16x32_bf16 v[46:49], v[114:117], v[170:173], v[46:49]
	v_mfma_f32_16x16x32_bf16 v[42:45], v[138:141], v[170:173], v[42:45]
	v_mfma_f32_16x16x32_bf16 v[30:33], v[114:117], v[178:181], v[30:33]
	v_mfma_f32_16x16x32_bf16 v[26:29], v[138:141], v[178:181], v[26:29]
	v_mfma_f32_16x16x32_bf16 v[14:17], v[114:117], v[206:209], v[14:17]
	v_mfma_f32_16x16x32_bf16 v[10:13], v[138:141], v[206:209], v[10:13]
	v_mfma_f32_16x16x32_bf16 v[62:65], v[126:129], v[166:169], v[62:65]
	v_mfma_f32_16x16x32_bf16 v[58:61], v[142:145], v[166:169], v[58:61]
	v_mfma_f32_16x16x32_bf16 v[46:49], v[126:129], v[174:177], v[46:49]
	v_mfma_f32_16x16x32_bf16 v[42:45], v[142:145], v[174:177], v[42:45]
	v_mfma_f32_16x16x32_bf16 v[30:33], v[126:129], v[182:185], v[30:33]
	v_mfma_f32_16x16x32_bf16 v[26:29], v[142:145], v[182:185], v[26:29]
	v_mfma_f32_16x16x32_bf16 v[14:17], v[126:129], v[210:213], v[14:17]
	v_mfma_f32_16x16x32_bf16 v[10:13], v[142:145], v[210:213], v[10:13]
	s_setprio 0
	s_setprio 1
	v_mfma_f32_16x16x32_bf16 v[54:57], v[146:149], v[162:165], v[54:57]
	v_mfma_f32_16x16x32_bf16 v[50:53], v[154:157], v[162:165], v[50:53]
	v_mfma_f32_16x16x32_bf16 v[38:41], v[146:149], v[170:173], v[38:41]
	v_mfma_f32_16x16x32_bf16 v[34:37], v[154:157], v[170:173], v[34:37]
	v_mfma_f32_16x16x32_bf16 v[22:25], v[146:149], v[178:181], v[22:25]
	v_mfma_f32_16x16x32_bf16 v[18:21], v[154:157], v[178:181], v[18:21]
	v_mfma_f32_16x16x32_bf16 v[6:9], v[146:149], v[206:209], v[6:9]
	v_mfma_f32_16x16x32_bf16 v[2:5], v[154:157], v[206:209], v[2:5]
	v_mfma_f32_16x16x32_bf16 v[54:57], v[150:153], v[166:169], v[54:57]
	v_mfma_f32_16x16x32_bf16 v[50:53], v[158:161], v[166:169], v[50:53]
	v_mfma_f32_16x16x32_bf16 v[38:41], v[150:153], v[174:177], v[38:41]
	v_mfma_f32_16x16x32_bf16 v[34:37], v[158:161], v[174:177], v[34:37]
	v_mfma_f32_16x16x32_bf16 v[22:25], v[150:153], v[182:185], v[22:25]
	v_mfma_f32_16x16x32_bf16 v[18:21], v[158:161], v[182:185], v[18:21]
	v_mfma_f32_16x16x32_bf16 v[6:9], v[150:153], v[210:213], v[6:9]
	v_mfma_f32_16x16x32_bf16 v[2:5], v[158:161], v[210:213], v[2:5]
	s_setprio 0
	s_barrier
	s_add_i32 s72, 0, 0x18000
	s_add_i32 s73, 0, 0x1c000
	v_add_u32_e32 v142, s72, v224
	v_add_u32_e32 v158, s73, v224
	ds_read_b128 v[114:117], v142
	ds_read_b128 v[126:129], v142 offset:1024
	ds_read_b128 v[138:141], v142 offset:2048
	ds_read_b128 v[142:145], v142 offset:3072
	ds_read_b128 v[146:149], v158
	ds_read_b128 v[150:153], v158 offset:1024
	ds_read_b128 v[154:157], v158 offset:2048
	ds_read_b128 v[158:161], v158 offset:3072
	s_add_u32 s44, s50, 0xb0000
	s_addc_u32 s45, s51, 0
	s_mov_b32 m0, s55
	v_lshl_add_u64 v[222:223], s[44:45], 0, v[186:187]
	ds_read_b128 v[162:165], v227 offset:32768
	ds_read_b128 v[166:169], v227 offset:33792
	ds_read_b128 v[170:173], v227 offset:34816
	ds_read_b128 v[174:177], v227 offset:35840
	ds_read_b128 v[178:181], v227 offset:36864
	ds_read_b128 v[182:185], v227 offset:37888
	ds_read_b128 v[206:209], v227 offset:38912
	ds_read_b128 v[210:213], v227 offset:39936
	global_load_lds_dwordx4 v[222:223], off
	v_lshl_add_u64 v[222:223], s[44:45], 0, v[190:191]
	s_mov_b32 m0, s56
	s_nop 0
	global_load_lds_dwordx4 v[222:223], off
	s_waitcnt vmcnt(8)
	s_waitcnt lgkmcnt(0)
	s_setprio 1
	s_barrier
	v_mfma_f32_16x16x32_bf16 v[134:137], v[114:117], v[162:165], v[134:137]
	v_mfma_f32_16x16x32_bf16 v[130:133], v[138:141], v[162:165], v[130:133]
	v_mfma_f32_16x16x32_bf16 v[110:113], v[114:117], v[170:173], v[110:113]
	v_mfma_f32_16x16x32_bf16 v[106:109], v[138:141], v[170:173], v[106:109]
	v_mfma_f32_16x16x32_bf16 v[94:97], v[114:117], v[178:181], v[94:97]
	v_mfma_f32_16x16x32_bf16 v[90:93], v[138:141], v[178:181], v[90:93]
	v_mfma_f32_16x16x32_bf16 v[78:81], v[114:117], v[206:209], v[78:81]
	v_mfma_f32_16x16x32_bf16 v[74:77], v[138:141], v[206:209], v[74:77]
	v_mfma_f32_16x16x32_bf16 v[134:137], v[126:129], v[166:169], v[134:137]
	v_mfma_f32_16x16x32_bf16 v[130:133], v[142:145], v[166:169], v[130:133]
	v_mfma_f32_16x16x32_bf16 v[110:113], v[126:129], v[174:177], v[110:113]
	v_mfma_f32_16x16x32_bf16 v[106:109], v[142:145], v[174:177], v[106:109]
	v_mfma_f32_16x16x32_bf16 v[94:97], v[126:129], v[182:185], v[94:97]
	v_mfma_f32_16x16x32_bf16 v[90:93], v[142:145], v[182:185], v[90:93]
	v_mfma_f32_16x16x32_bf16 v[78:81], v[126:129], v[210:213], v[78:81]
	v_mfma_f32_16x16x32_bf16 v[74:77], v[142:145], v[210:213], v[74:77]
	s_setprio 0
	s_setprio 1
	v_mfma_f32_16x16x32_bf16 v[122:125], v[146:149], v[162:165], v[122:125]
	v_mfma_f32_16x16x32_bf16 v[118:121], v[154:157], v[162:165], v[118:121]
	v_mfma_f32_16x16x32_bf16 v[102:105], v[146:149], v[170:173], v[102:105]
	v_mfma_f32_16x16x32_bf16 v[98:101], v[154:157], v[170:173], v[98:101]
	v_mfma_f32_16x16x32_bf16 v[86:89], v[146:149], v[178:181], v[86:89]
	v_mfma_f32_16x16x32_bf16 v[82:85], v[154:157], v[178:181], v[82:85]
	v_mfma_f32_16x16x32_bf16 v[70:73], v[146:149], v[206:209], v[70:73]
	v_mfma_f32_16x16x32_bf16 v[66:69], v[154:157], v[206:209], v[66:69]
	v_mfma_f32_16x16x32_bf16 v[122:125], v[150:153], v[166:169], v[122:125]
	v_mfma_f32_16x16x32_bf16 v[118:121], v[158:161], v[166:169], v[118:121]
	v_mfma_f32_16x16x32_bf16 v[102:105], v[150:153], v[174:177], v[102:105]
	v_mfma_f32_16x16x32_bf16 v[98:101], v[158:161], v[174:177], v[98:101]
	v_mfma_f32_16x16x32_bf16 v[86:89], v[150:153], v[182:185], v[86:89]
	v_mfma_f32_16x16x32_bf16 v[82:85], v[158:161], v[182:185], v[82:85]
	v_mfma_f32_16x16x32_bf16 v[70:73], v[150:153], v[210:213], v[70:73]
	v_mfma_f32_16x16x32_bf16 v[66:69], v[158:161], v[210:213], v[66:69]
	s_setprio 0
	s_barrier
	s_add_i32 s44, s72, s52
	v_lshl_add_u64 v[214:215], v[214:215], 0, s[24:25]
	s_mov_b32 m0, s44
	ds_read_b128 v[162:165], v227 offset:49152
	ds_read_b128 v[166:169], v227 offset:50176
	ds_read_b128 v[170:173], v227 offset:51200
	ds_read_b128 v[174:177], v227 offset:52224
	ds_read_b128 v[178:181], v227 offset:53248
	ds_read_b128 v[182:185], v227 offset:54272
	ds_read_b128 v[206:209], v227 offset:55296
	ds_read_b128 v[210:213], v227 offset:56320
	global_load_lds_dwordx4 v[214:215], off
	s_add_i32 m0, s44, 0x2000
	s_add_u32 s44, s48, 0xb0080
	v_lshl_add_u64 v[214:215], v[216:217], 0, s[24:25]
	s_addc_u32 s45, s49, 0
	s_add_i32 s48, s73, s52
	global_load_lds_dwordx4 v[214:215], off
	v_lshl_add_u64 v[214:215], s[44:45], 0, v[188:189]
	s_mov_b32 m0, s48
	s_nop 0
	global_load_lds_dwordx4 v[214:215], off
	v_lshl_add_u64 v[214:215], s[44:45], 0, v[192:193]
	s_add_i32 m0, s48, 0x2000
	s_nop 0
	global_load_lds_dwordx4 v[214:215], off
	v_lshl_add_u64 v[214:215], v[218:219], 0, s[24:25]
	s_mov_b32 m0, s58
	s_nop 0
	global_load_lds_dwordx4 v[214:215], off
	v_lshl_add_u64 v[214:215], v[220:221], 0, s[24:25]
	s_mov_b32 m0, s59
	s_nop 0
	global_load_lds_dwordx4 v[214:215], off
	s_waitcnt vmcnt(8)
	s_waitcnt lgkmcnt(0)
	s_setprio 1
	s_barrier
	v_mfma_f32_16x16x32_bf16 v[62:65], v[114:117], v[162:165], v[62:65]
	v_mfma_f32_16x16x32_bf16 v[58:61], v[138:141], v[162:165], v[58:61]
	v_mfma_f32_16x16x32_bf16 v[46:49], v[114:117], v[170:173], v[46:49]
	v_mfma_f32_16x16x32_bf16 v[42:45], v[138:141], v[170:173], v[42:45]
	v_mfma_f32_16x16x32_bf16 v[30:33], v[114:117], v[178:181], v[30:33]
	v_mfma_f32_16x16x32_bf16 v[26:29], v[138:141], v[178:181], v[26:29]
	v_mfma_f32_16x16x32_bf16 v[14:17], v[114:117], v[206:209], v[14:17]
	v_mfma_f32_16x16x32_bf16 v[10:13], v[138:141], v[206:209], v[10:13]
	v_mfma_f32_16x16x32_bf16 v[62:65], v[126:129], v[166:169], v[62:65]
	v_mfma_f32_16x16x32_bf16 v[58:61], v[142:145], v[166:169], v[58:61]
	v_mfma_f32_16x16x32_bf16 v[46:49], v[126:129], v[174:177], v[46:49]
	v_mfma_f32_16x16x32_bf16 v[42:45], v[142:145], v[174:177], v[42:45]
	v_mfma_f32_16x16x32_bf16 v[30:33], v[126:129], v[182:185], v[30:33]
	v_mfma_f32_16x16x32_bf16 v[26:29], v[142:145], v[182:185], v[26:29]
	v_mfma_f32_16x16x32_bf16 v[14:17], v[126:129], v[210:213], v[14:17]
	v_mfma_f32_16x16x32_bf16 v[10:13], v[142:145], v[210:213], v[10:13]
	s_setprio 0
	s_setprio 1
	v_mfma_f32_16x16x32_bf16 v[54:57], v[146:149], v[162:165], v[54:57]
	v_mfma_f32_16x16x32_bf16 v[50:53], v[154:157], v[162:165], v[50:53]
	v_mfma_f32_16x16x32_bf16 v[38:41], v[146:149], v[170:173], v[38:41]
	v_mfma_f32_16x16x32_bf16 v[34:37], v[154:157], v[170:173], v[34:37]
	v_mfma_f32_16x16x32_bf16 v[22:25], v[146:149], v[178:181], v[22:25]
	v_mfma_f32_16x16x32_bf16 v[18:21], v[154:157], v[178:181], v[18:21]
	v_mfma_f32_16x16x32_bf16 v[6:9], v[146:149], v[206:209], v[6:9]
	v_mfma_f32_16x16x32_bf16 v[2:5], v[154:157], v[206:209], v[2:5]
	v_mfma_f32_16x16x32_bf16 v[54:57], v[150:153], v[166:169], v[54:57]
	v_mfma_f32_16x16x32_bf16 v[50:53], v[158:161], v[166:169], v[50:53]
	v_mfma_f32_16x16x32_bf16 v[38:41], v[150:153], v[174:177], v[38:41]
	v_mfma_f32_16x16x32_bf16 v[34:37], v[158:161], v[174:177], v[34:37]
	v_mfma_f32_16x16x32_bf16 v[22:25], v[150:153], v[182:185], v[22:25]
	v_mfma_f32_16x16x32_bf16 v[18:21], v[158:161], v[182:185], v[18:21]
	v_mfma_f32_16x16x32_bf16 v[6:9], v[150:153], v[210:213], v[6:9]
	v_mfma_f32_16x16x32_bf16 v[2:5], v[158:161], v[210:213], v[2:5]
	s_setprio 0
	s_barrier
	s_add_i32 s71, s71, 2
	s_add_u32 s69, s69, 0x100
	s_addc_u32 s70, s70, 0
	s_cmp_gt_u32 s71, 41
	s_mov_b64 s[44:45], s[46:47]
	s_cbranch_scc0 .LBB0_1909
	v_lshl_add_u32 v222, s67, 8, v195
	s_lshl_b32 s44, s68, 8
	s_ashr_i32 s45, s44, 31
	v_ashrrev_i32_e32 v223, 31, v222
	v_lshl_add_u64 v[114:115], s[44:45], 1, v[196:197]
	v_lshlrev_b64 v[116:117], 11, v[222:223]
	v_lshl_add_u64 v[116:117], v[114:115], 0, v[116:117]
	global_load_dwordx4 v[230:233], v[116:117], off
	global_load_dwordx4 v[234:237], v[116:117], off offset:256
	v_or_b32_e32 v220, 16, v222
	v_or_b32_e32 v218, 32, v222
	v_or_b32_e32 v216, 48, v222
	v_add_u32_e32 v214, 0x80, v222
	v_add_u32_e32 v212, 0x90, v222
	v_add_u32_e32 v210, 0xa0, v222
	v_add_u32_e32 v206, 0xb0, v222
	v_ashrrev_i32_e32 v221, 31, v220
	v_ashrrev_i32_e32 v219, 31, v218
	v_ashrrev_i32_e32 v217, 31, v216
	v_ashrrev_i32_e32 v215, 31, v214
	v_ashrrev_i32_e32 v213, 31, v212
	v_ashrrev_i32_e32 v211, 31, v210
	v_ashrrev_i32_e32 v207, 31, v206
	v_lshlrev_b64 v[116:117], 11, v[220:221]
	v_lshlrev_b64 v[126:127], 11, v[218:219]
	v_lshlrev_b64 v[128:129], 11, v[216:217]
	v_lshlrev_b64 v[138:139], 11, v[214:215]
	v_lshlrev_b64 v[140:141], 11, v[212:213]
	v_lshlrev_b64 v[142:143], 11, v[210:211]
	v_lshlrev_b64 v[144:145], 11, v[206:207]
	v_lshl_add_u64 v[116:117], v[114:115], 0, v[116:117]
	v_lshl_add_u64 v[126:127], v[114:115], 0, v[126:127]
	v_lshl_add_u64 v[128:129], v[114:115], 0, v[128:129]
	v_lshl_add_u64 v[138:139], v[114:115], 0, v[138:139]
	v_lshl_add_u64 v[140:141], v[114:115], 0, v[140:141]
	v_lshl_add_u64 v[208:209], v[114:115], 0, v[142:143]
	v_lshl_add_u64 v[114:115], v[114:115], 0, v[144:145]
	global_load_dwordx4 v[182:185], v[116:117], off
	global_load_dwordx4 v[178:181], v[116:117], off offset:256
	global_load_dwordx4 v[174:177], v[126:127], off
	global_load_dwordx4 v[170:173], v[126:127], off offset:256
	global_load_dwordx4 v[166:169], v[128:129], off
	global_load_dwordx4 v[162:165], v[128:129], off offset:256
	global_load_dwordx4 v[158:161], v[138:139], off
	global_load_dwordx4 v[154:157], v[138:139], off offset:256
	global_load_dwordx4 v[150:153], v[140:141], off
	global_load_dwordx4 v[146:149], v[140:141], off offset:256
	global_load_dwordx4 v[142:145], v[208:209], off
	s_nop 0
	global_load_dwordx4 v[138:141], v[208:209], off offset:256
	global_load_dwordx4 v[126:129], v[114:115], off
	s_nop 0
	global_load_dwordx4 v[114:117], v[114:115], off offset:256
	s_and_b64 vcc, exec, s[26:27]
	s_cbranch_vccz .LBB0_1912
	s_barrier
.LBB0_1912:
	v_and_b32_e32 v209, 64, v228
	v_xor_b32_e32 v229, 16, v228
	v_add_u32_e32 v239, 64, v209
	v_xor_b32_e32 v238, 32, v228
	v_cmp_lt_i32_e32 vcc, v229, v239
	v_or_b32_e32 v208, s44, v194
	v_mov_b32_e32 v209, s45
	v_cndmask_b32_e32 v229, v228, v229, vcc
	v_cmp_lt_i32_e32 vcc, v238, v239
	v_lshlrev_b32_e32 v229, 2, v229
	s_waitcnt vmcnt(0)
	v_and_b32_e32 v239, 0xffff0000, v230
	v_cndmask_b32_e32 v243, v228, v238, vcc
	v_lshlrev_b32_e32 v238, 16, v230
	v_lshlrev_b32_e32 v230, 16, v231
	v_and_b32_e32 v231, 0xffff0000, v231
	v_lshlrev_b32_e32 v240, 16, v232
	v_and_b32_e32 v241, 0xffff0000, v232
	v_lshlrev_b32_e32 v232, 16, v233
	v_and_b32_e32 v233, 0xffff0000, v233
	v_pk_fma_f32 v[136:137], v[136:137], 0.5, v[230:231] op_sel_hi:[1,0,1]
	v_pk_fma_f32 v[134:135], v[134:135], 0.5, v[238:239] op_sel_hi:[1,0,1]
	v_pk_fma_f32 v[132:133], v[132:133], 0.5, v[232:233] op_sel_hi:[1,0,1]
	v_pk_fma_f32 v[130:131], v[130:131], 0.5, v[240:241] op_sel_hi:[1,0,1]
	v_mul_f32_e32 v230, v135, v135
	v_mul_f32_e32 v231, v137, v137
	v_mul_f32_e32 v232, v131, v131
	v_mul_f32_e32 v233, v133, v133
	v_fmac_f32_e32 v230, v134, v134
	v_fmac_f32_e32 v231, v136, v136
	v_fmac_f32_e32 v232, v130, v130
	v_fmac_f32_e32 v233, v132, v132
	v_lshlrev_b32_e32 v244, 16, v234
	v_and_b32_e32 v245, 0xffff0000, v234
	v_lshlrev_b32_e32 v234, 16, v235
	v_and_b32_e32 v235, 0xffff0000, v235
	v_add_f32_e32 v230, v230, v231
	v_add_f32_e32 v231, v232, v233
	v_lshlrev_b32_e32 v246, 16, v236
	v_add_f32_e32 v238, v230, v231
	v_and_b32_e32 v247, 0xffff0000, v236
	v_lshlrev_b32_e32 v230, 16, v237
	v_and_b32_e32 v231, 0xffff0000, v237
	v_pk_fma_f32 v[124:125], v[124:125], 0.5, v[234:235] op_sel_hi:[1,0,1]
	v_pk_fma_f32 v[122:123], v[122:123], 0.5, v[244:245] op_sel_hi:[1,0,1]
	v_pk_fma_f32 v[232:233], v[120:121], 0.5, v[230:231] op_sel_hi:[1,0,1]
	v_pk_fma_f32 v[230:231], v[118:119], 0.5, v[246:247] op_sel_hi:[1,0,1]
	v_mul_f32_e32 v118, v123, v123
	v_mul_f32_e32 v119, v125, v125
	v_fmac_f32_e32 v118, v122, v122
	v_fmac_f32_e32 v119, v124, v124
	v_add_f32_e32 v118, v118, v119
	v_mul_f32_e32 v119, v231, v231
	v_mul_f32_e32 v120, v233, v233
	v_fmac_f32_e32 v119, v230, v230
	v_fmac_f32_e32 v120, v232, v232
	v_add_f32_e32 v119, v119, v120
	v_add_f32_e32 v118, v118, v119
	v_add_f32_e32 v119, v238, v118
	v_mov_b32_e32 v236, v119
	s_nop 1
	v_permlane16_swap_b32_e32 v236, v119
	v_lshlrev_b64 v[120:121], 12, v[222:223]
	v_lshlrev_b32_e32 v118, 2, v243
	v_lshl_add_u64 v[120:121], s[12:13], 0, v[120:121]
	v_lshl_add_u64 v[234:235], v[208:209], 2, v[120:121]
	s_waitcnt lgkmcnt(0)
	v_add_f32_e32 v119, v119, v236
	v_mov_b32_e32 v120, v119
	s_nop 1
	v_permlane32_swap_b32_e32 v120, v119
	global_store_dwordx4 v[234:235], v[134:137], off
	global_store_dwordx4 v[234:235], v[130:133], off offset:16
	global_store_dwordx4 v[234:235], v[122:125], off offset:512
	global_store_dwordx4 v[234:235], v[230:233], off offset:528
	s_and_saveexec_b64 s[44:45], s[4:5]
	s_cbranch_execz .LBB0_1914
	v_lshl_add_u64 v[122:123], v[222:223], 2, s[16:17]
	s_waitcnt lgkmcnt(0)
	v_add_f32_e32 v119, v119, v120
	global_atomic_add_f32 v[122:123], v119, off
